# latency stack: GLA-intra counted load waits, gla_inter epilogue loads issued behind the main loads (counted waits +16), P1 second table loop with 16 partial loads in flight
# speedup vs baseline: 1.0054x; 1.0054x over previous
; __device__ __forceinline__ void p1_rows(const Params& P, LAS unsigned char* lds, int G) {
;     ...
;     for (int idx = blockIdx.x * NTHREADS + tid; idx < 2 * NADA; idx += G * NTHREADS) { const int b = idx / NADA, n = idx % NADA; float v = P.b_ada[n];
;         for (int ks = 0; ks < KS_ADA; ++ks) v += adap[(size_t)(ks * 2 + b) * NADA + n];
;         ada[idx] = v; }
.LBB0_163:
	v_mul_hi_i32 v1, v0, s10
	v_lshrrev_b32_e32 v2, 31, v1
	v_ashrrev_i32_e32 v1, 11, v1
	v_add_u32_e32 v1, v1, v2
	v_mul_i32_i24_e32 v2, 0x3000, v1
	v_sub_u32_e32 v2, v0, v2
	v_ashrrev_i32_e32 v3, 31, v2
	v_lshlrev_b64 v[2:3], 2, v[2:3]
	v_lshl_add_u64 v[4:5], s[68:69], 0, v[2:3]
	global_load_dword v4, v[4:5], off
	v_mad_i64_i32 v[2:3], s[8:9], v1, s11, v[2:3]
	global_load_dword v14, v2, s[58:59]
	s_add_u32 s100, s58, 0x18000
	s_addc_u32 s101, s59, 0
	global_load_dword v15, v2, s[100:101]
	s_add_u32 s100, s58, 0x30000
	s_addc_u32 s101, s59, 0
	global_load_dword v16, v2, s[100:101]
	s_add_u32 s100, s58, 0x48000
	s_addc_u32 s101, s59, 0
	global_load_dword v17, v2, s[100:101]
	s_add_u32 s100, s58, 0x60000
	s_addc_u32 s101, s59, 0
	global_load_dword v18, v2, s[100:101]
	s_add_u32 s100, s58, 0x78000
	s_addc_u32 s101, s59, 0
	global_load_dword v19, v2, s[100:101]
	s_add_u32 s100, s58, 0x90000
	s_addc_u32 s101, s59, 0
	global_load_dword v20, v2, s[100:101]
	s_add_u32 s100, s58, 0xa8000
	s_addc_u32 s101, s59, 0
	global_load_dword v21, v2, s[100:101]
	s_add_u32 s100, s58, 0xc0000
	s_addc_u32 s101, s59, 0
	global_load_dword v22, v2, s[100:101]
	s_add_u32 s100, s58, 0xd8000
	s_addc_u32 s101, s59, 0
	global_load_dword v23, v2, s[100:101]
	s_add_u32 s100, s58, 0xf0000
	s_addc_u32 s101, s59, 0
	global_load_dword v24, v2, s[100:101]
	s_add_u32 s100, s58, 0x108000
	s_addc_u32 s101, s59, 0
	global_load_dword v25, v2, s[100:101]
	s_add_u32 s100, s58, 0x120000
	s_addc_u32 s101, s59, 0
	global_load_dword v26, v2, s[100:101]
	s_add_u32 s100, s58, 0x138000
	s_addc_u32 s101, s59, 0
	global_load_dword v27, v2, s[100:101]
	s_add_u32 s100, s58, 0x150000
	s_addc_u32 s101, s59, 0
	global_load_dword v28, v2, s[100:101]
	s_add_u32 s100, s58, 0x168000
	s_addc_u32 s101, s59, 0
	global_load_dword v29, v2, s[100:101]
	s_waitcnt vmcnt(15)
	v_add_f32_e32 v1, v4, v14
	s_waitcnt vmcnt(14)
	v_add_f32_e32 v1, v1, v15
	s_waitcnt vmcnt(13)
	v_add_f32_e32 v1, v1, v16
	s_waitcnt vmcnt(12)
	v_add_f32_e32 v1, v1, v17
	s_waitcnt vmcnt(11)
	v_add_f32_e32 v1, v1, v18
	s_waitcnt vmcnt(10)
	v_add_f32_e32 v1, v1, v19
	s_waitcnt vmcnt(9)
	v_add_f32_e32 v1, v1, v20
	s_waitcnt vmcnt(8)
	v_add_f32_e32 v1, v1, v21
	s_waitcnt vmcnt(7)
	v_add_f32_e32 v1, v1, v22
	s_waitcnt vmcnt(6)
	v_add_f32_e32 v1, v1, v23
	s_waitcnt vmcnt(5)
	v_add_f32_e32 v1, v1, v24
	s_waitcnt vmcnt(4)
	v_add_f32_e32 v1, v1, v25
	s_waitcnt vmcnt(3)
	v_add_f32_e32 v1, v1, v26
	s_waitcnt vmcnt(2)
	v_add_f32_e32 v1, v1, v27
	s_waitcnt vmcnt(1)
	v_add_f32_e32 v1, v1, v28
	s_waitcnt vmcnt(0)
	v_add_f32_e32 v4, v1, v29
	v_ashrrev_i32_e32 v1, 31, v0
	v_lshl_add_u64 v[2:3], v[0:1], 2, s[14:15]
	v_add_u32_e32 v0, s33, v0
	v_cmp_lt_i32_e32 vcc, s12, v0
	s_or_b64 s[6:7], vcc, s[6:7]
	global_store_dword v[2:3], v4, off
	s_andn2_b64 exec, exec, s[6:7]
	s_cbranch_execnz .LBB0_163

; __device__ __forceinline__ void gla_intra_unit(const Params& P, LAS unsigned char* lds, int unit) {
;     ...
;     for (int r = 0; r < 16; ++r) wg_[r] = P.w_gate_up[r * 512 + 128 * h + d_];
;     const float bias_ = P.b_gate[128 * h + d_];
;     bf16_t qraw_[16], kraw_[16];
; #pragma unroll
;     for (int i = 0; i < 16; ++i) { const size_t zr = (t0 + cgp_ * 16 + i) * ZC; qraw_[i] = Z[zr + ZO_QG + 128 * h + d_]; kraw_[i] = Z[zr + ZO_KG + 128 * h + d_]; }
;     { const int idx = tid * 2, c = idx >> 4, r = idx & 15; const unsigned w = *(const unsigned*)(Z + (t0 + c) * ZC + ZO_AG + r); ag[c * 16 + r] = __uint_as_float(w << 16); ag[c * 16 + r + 1] = __uint_as_float(w & 0xffff0000u); }
.LBB0_424:
	v_mov_b32_e32 v0, v168
	s_ashr_i32 s64, s66, 9
	s_bfe_u32 s1, s66, 0x20007
	v_and_b32_e32 v2, 0x7f, v0
	s_ashr_i32 s65, s64, 31
	s_lshl_b32 s0, s1, 9
	v_lshlrev_b32_e32 v28, 2, v2
	v_ashrrev_i32_e32 v24, 7, v0
	s_and_b32 s38, s22, 0x1fc0
	v_or_b32_e32 v104, s0, v28
	s_lshl_b64 s[64:65], s[64:65], 13
	v_lshlrev_b32_e32 v6, 4, v24
	v_lshl_add_u64 v[16:17], s[86:87], 0, v[104:105]
	s_or_b32 s64, s64, s38
	v_ashrrev_i32_e32 v7, 31, v6
	v_add_co_u32_e32 v4, vcc, s26, v16
	v_lshl_add_u64 v[18:19], s[64:65], 0, v[6:7]
	s_nop 0
	v_addc_co_u32_e32 v5, vcc, 0, v17, vcc
	v_lshlrev_b64 v[18:19], 13, v[18:19]
	v_add_co_u32_e32 v14, vcc, s27, v16
	v_lshl_add_u64 v[18:19], s[56:57], 0, v[18:19]
	s_lshl_b32 s38, s1, 8
	v_ashrrev_i32_e32 v26, 3, v0
	v_addc_co_u32_e32 v15, vcc, 0, v17, vcc
	global_load_dword v10, v104, s[86:87]
	global_load_dword v12, v104, s[86:87] offset:2048
	global_load_dword v8, v[4:5], off offset:-4096
	global_load_dword v11, v[4:5], off
	global_load_dword v13, v[4:5], off offset:2048
	global_load_dword v9, v[14:15], off offset:-4096
	s_nop 0
	global_load_dword v4, v[14:15], off
	global_load_dword v49, v104, s[88:89]
	v_lshl_add_u64 v[18:19], v[18:19], 0, s[38:39]
	v_lshlrev_b32_e32 v104, 1, v2
	v_ashrrev_i32_e32 v27, 31, v26
	v_lshl_add_u64 v[22:23], v[18:19], 0, v[104:105]
	v_lshlrev_b32_e32 v1, 1, v0
	v_lshl_add_u64 v[18:19], s[64:65], 0, v[26:27]
	v_and_b32_e32 v1, 14, v1
	v_lshlrev_b64 v[18:19], 13, v[18:19]
	v_lshl_add_u64 v[18:19], s[56:57], 0, v[18:19]
	v_lshlrev_b32_e32 v104, 1, v1
	v_lshl_add_u64 v[18:19], v[18:19], 0, v[104:105]
	v_add_co_u32_e32 v18, vcc, s3, v18
	s_movk_i32 s1, 0x3000
	s_nop 0
	v_addc_co_u32_e32 v19, vcc, 0, v19, vcc
	global_load_dword v3, v[18:19], off offset:3712
	v_add_co_u32_e32 v20, vcc, s3, v16
	v_and_b32_e32 v92, 63, v0
	s_nop 0
	v_addc_co_u32_e32 v21, vcc, 0, v17, vcc
	v_add_co_u32_e32 v30, vcc, s1, v16
	s_movk_i32 s1, 0x5000
	s_nop 0
	v_addc_co_u32_e32 v31, vcc, 0, v17, vcc
	v_add_co_u32_e32 v32, vcc, s1, v16
	s_movk_i32 s1, 0x7000
	s_nop 0
	v_addc_co_u32_e32 v33, vcc, 0, v17, vcc
	v_add_co_u32_e32 v34, vcc, s33, v16
	v_or_b32_e32 v46, s64, v92
	s_nop 0
	v_addc_co_u32_e32 v35, vcc, 0, v17, vcc
	global_load_dword v18, v[14:15], off offset:2048
	s_nop 0
	global_load_dword v14, v[34:35], off offset:-4096
	global_load_dword v5, v[34:35], off
	global_load_dword v19, v[34:35], off offset:2048
	v_add_co_u32_e32 v34, vcc, s1, v16
	s_mov_b32 s1, 0x8000
	s_nop 0
	v_addc_co_u32_e32 v35, vcc, 0, v17, vcc
	global_load_dword v20, v[20:21], off offset:2048
	s_nop 0
	global_load_dword v21, v[30:31], off offset:2048
	global_load_dword v16, v[32:33], off offset:2048
	global_load_dword v15, v[34:35], off
	global_load_dword v17, v[34:35], off offset:2048
	v_add_co_u32_e32 v30, vcc, s26, v22
	v_mov_b32_e32 v47, s65
	s_nop 0
	v_addc_co_u32_e32 v31, vcc, 0, v23, vcc
	v_add_co_u32_e32 v32, vcc, s27, v22
	v_lshlrev_b32_e32 v7, 6, v26
	s_nop 0
	v_addc_co_u32_e32 v33, vcc, 0, v23, vcc
	v_add_co_u32_e32 v38, vcc, s33, v22
	v_lshlrev_b32_e32 v1, 2, v1
	s_nop 0
	v_addc_co_u32_e32 v39, vcc, 0, v23, vcc
	global_load_ushort v52, v[22:23], off offset:1536
	global_load_ushort v43, v[30:31], off offset:1536
	global_load_ushort v40, v[30:31], off offset:2560
	global_load_ushort v36, v[32:33], off offset:1536
	global_load_ushort v34, v[38:39], off offset:1536
	s_nop 0
	global_load_ushort v33, v[32:33], off offset:2560
	s_nop 0
	global_load_ushort v41, v[22:23], off offset:2560
	v_add_co_u32_e32 v30, vcc, s1, v22
	s_mov_b32 s1, 0xa000
	s_nop 0
	v_addc_co_u32_e32 v31, vcc, 0, v23, vcc
	v_add_co_u32_e32 v44, vcc, s1, v22
	s_mov_b32 s1, 0x1e000
	s_nop 0
	v_addc_co_u32_e32 v45, vcc, 0, v23, vcc
	v_lshlrev_b64 v[46:47], 13, v[46:47]
	v_add3_u32 v55, 0, v7, v1
	v_add_co_u32_e32 v74, vcc, s1, v22
	v_lshl_add_u64 v[46:47], s[56:57], 0, v[46:47]
	s_mov_b32 s1, s39
	v_and_b32_e32 v76, -8, v26
	v_addc_co_u32_e32 v75, vcc, 0, v23, vcc
	v_lshl_add_u64 v[46:47], v[46:47], 0, s[0:1]
	v_ashrrev_i32_e32 v77, 31, v76
	v_lshl_add_u64 v[26:27], v[76:77], 1, v[46:47]
	global_load_ushort v1, v[74:75], off offset:2560
	global_load_dwordx4 v[56:59], v[26:27], off offset:3584
	s_mov_b32 s0, 0xc000
	v_add_co_u32_e32 v26, vcc, s0, v22
	s_mov_b32 s0, 0xe000
	s_nop 0
	v_addc_co_u32_e32 v27, vcc, 0, v23, vcc
	v_add_co_u32_e32 v80, vcc, s0, v22
	s_mov_b32 s0, 0x10000
	s_nop 0
	v_addc_co_u32_e32 v81, vcc, 0, v23, vcc
	s_waitcnt vmcnt(18)
; __device__ __forceinline__ void gla_intra_unit(const Params& P, LAS unsigned char* lds, int unit) {
;     ...
;     { const int idx = tid * 2, c = idx >> 4, r = idx & 15; const unsigned w = *(const unsigned*)(Z + (t0 + c) * ZC + ZO_AG + r); ag[c * 16 + r] = __uint_as_float(w << 16); ag[c * 16 + r + 1] = __uint_as_float(w & 0xffff0000u); }
; #pragma unroll
;     for (int i = 0; i < 4; ++i) { const int id = tid + NTHREADS * i, c = id & 63, vc = id >> 6;
;         const u32x4 w = *(const u32x4*)(Z + (t0 + c) * ZC + ZO_VG + 256 * h + 8 * vc);
; #pragma unroll
;         for (int e = 0; e < 4; ++e) { vT[(8 * vc + 2 * e) * 72 + c] = (bf16_t)(w[e] & 0xffffu); vT[(8 * vc + 2 * e + 1) * 72 + c] = (bf16_t)(w[e] >> 16); } }
;     __syncthreads();
	v_lshlrev_b32_e32 v72, 16, v3
	v_and_b32_e32 v73, 0xffff0000, v3
	v_add_u32_e32 v3, 0x200, v0
	v_ashrrev_i32_e32 v7, 3, v3
	v_and_b32_e32 v78, -8, v7
	v_add_u32_e32 v7, 0x400, v0
	v_ashrrev_i32_e32 v79, 31, v78
	v_ashrrev_i32_e32 v7, 3, v7
	v_lshl_add_u64 v[50:51], v[78:79], 1, v[46:47]
	v_and_b32_e32 v82, -8, v7
	global_load_dwordx4 v[60:63], v[50:51], off offset:3584
	v_ashrrev_i32_e32 v83, 31, v82
	v_lshl_add_u64 v[50:51], v[82:83], 1, v[46:47]
	global_load_dwordx4 v[64:67], v[50:51], off offset:3584
	v_add_u32_e32 v7, 0x600, v0
	v_ashrrev_i32_e32 v7, 3, v7
	v_and_b32_e32 v84, -8, v7
	v_ashrrev_i32_e32 v85, 31, v84
	v_lshl_add_u64 v[46:47], v[84:85], 1, v[46:47]
	global_load_dwordx4 v[68:71], v[46:47], off offset:3584
	global_load_ushort v54, v[38:39], off offset:2560
	global_load_ushort v53, v[30:31], off offset:1536
	global_load_ushort v51, v[44:45], off offset:1536
	global_load_ushort v48, v[44:45], off offset:2560
	s_nop 0
	global_load_ushort v47, v[26:27], off offset:1536
	global_load_ushort v45, v[80:81], off offset:1536
	global_load_ushort v44, v[26:27], off offset:2560
	global_load_ushort v50, v[30:31], off offset:2560
	v_add_co_u32_e32 v26, vcc, s0, v22
	s_mov_b32 s0, 0x12000
	s_nop 0
	v_addc_co_u32_e32 v27, vcc, 0, v23, vcc
	v_add_co_u32_e32 v30, vcc, s0, v22
	s_mov_b32 s0, 0x14000
	s_nop 0
	v_addc_co_u32_e32 v31, vcc, 0, v23, vcc
	v_add_co_u32_e32 v86, vcc, s0, v22
	s_mov_b32 s0, 0x16000
	s_nop 0
	v_addc_co_u32_e32 v87, vcc, 0, v23, vcc
	v_add_co_u32_e32 v88, vcc, s0, v22
	s_mov_b32 s0, 0x18000
	s_nop 0
	v_addc_co_u32_e32 v89, vcc, 0, v23, vcc
	global_load_ushort v46, v[80:81], off offset:2560
	global_load_ushort v42, v[26:27], off offset:1536
	global_load_ushort v39, v[30:31], off offset:1536
	global_load_ushort v37, v[30:31], off offset:2560
	global_load_ushort v35, v[86:87], off offset:1536
	s_nop 0
	global_load_ushort v31, v[88:89], off offset:1536
	global_load_ushort v30, v[86:87], off offset:2560
	global_load_ushort v38, v[26:27], off offset:2560
	v_add_co_u32_e32 v80, vcc, s0, v22
	s_mov_b32 s0, 0x1a000
	s_nop 0
	v_addc_co_u32_e32 v81, vcc, 0, v23, vcc
	v_add_co_u32_e32 v86, vcc, s0, v22
	s_mov_b32 s0, 0x1c000
	s_nop 0
	v_addc_co_u32_e32 v87, vcc, 0, v23, vcc
	v_add_co_u32_e32 v90, vcc, s0, v22
	s_nop 1
	v_addc_co_u32_e32 v91, vcc, 0, v23, vcc
	global_load_ushort v32, v[88:89], off offset:2560
	global_load_ushort v29, v[80:81], off offset:1536
	global_load_ushort v27, v[86:87], off offset:1536
	global_load_ushort v25, v[86:87], off offset:2560
	global_load_ushort v23, v[90:91], off offset:1536
	global_load_ushort v22, v[74:75], off offset:1536
	global_load_ushort v7, v[90:91], off offset:2560
	global_load_ushort v26, v[80:81], off offset:2560
	ds_write_b64 v55, v[72:73]
	v_mul_lo_u32 v55, v76, s43
	v_lshlrev_b32_e32 v72, 1, v92
	v_add3_u32 v55, 0, v55, v72
	s_waitcnt vmcnt(27)
	ds_write_b16 v55, v56 offset:61440
	ds_write_b16_d16_hi v55, v56 offset:61584
	ds_write_b16 v55, v57 offset:61728
	ds_write_b16_d16_hi v55, v57 offset:61872
	ds_write_b16 v55, v58 offset:62016
	ds_write_b16_d16_hi v55, v58 offset:62160
	ds_write_b16 v55, v59 offset:62304
	ds_write_b16_d16_hi v55, v59 offset:62448
	v_mul_lo_u32 v55, v78, s43
	v_add3_u32 v55, 0, v55, v72
	s_waitcnt vmcnt(0)
	ds_write_b16 v55, v60 offset:61440
	ds_write_b16_d16_hi v55, v60 offset:61584
	ds_write_b16 v55, v61 offset:61728
	ds_write_b16_d16_hi v55, v61 offset:61872
	ds_write_b16 v55, v62 offset:62016
	ds_write_b16_d16_hi v55, v62 offset:62160
	ds_write_b16 v55, v63 offset:62304
	ds_write_b16_d16_hi v55, v63 offset:62448
	v_mul_lo_u32 v55, v82, s43
	v_add3_u32 v55, 0, v55, v72
	ds_write_b16 v55, v64 offset:61440
	ds_write_b16_d16_hi v55, v64 offset:61584
	ds_write_b16 v55, v65 offset:61728
	ds_write_b16_d16_hi v55, v65 offset:61872
	ds_write_b16 v55, v66 offset:62016
	ds_write_b16_d16_hi v55, v66 offset:62160
	ds_write_b16 v55, v67 offset:62304
	ds_write_b16_d16_hi v55, v67 offset:62448
	v_mul_lo_u32 v55, v84, s43
	v_add3_u32 v55, 0, v55, v72
	ds_write_b16 v55, v68 offset:61440
	ds_write_b16_d16_hi v55, v68 offset:61584
	ds_write_b16 v55, v69 offset:61728
	ds_write_b16_d16_hi v55, v69 offset:61872
	ds_write_b16 v55, v70 offset:62016
	ds_write_b16_d16_hi v55, v70 offset:62160
	ds_write_b16 v55, v71 offset:62304
	ds_write_b16_d16_hi v55, v71 offset:62448
	v_lshl_add_u32 v55, v24, 10, 0
	s_waitcnt lgkmcnt(0)
	s_barrier
; #define LAS __attribute__((address_space(3)))
; __device__ __forceinline__ void gla_intra_unit(const Params& P, LAS unsigned char* lds, int unit) {
;     ...
;     { const int d = d_, cgp = cgp_;
;       float (&w)[16] = wg_; const float bias = bias_;
;       float bcv[16]; float run = 0.f;
; #pragma unroll
;       for (int i = 0; i < 16; ++i) { const int c = cgp * 16 + i; float xg = bias;
; #pragma unroll
;           for (int r4 = 0; r4 < 4; ++r4) { const f32x4 a = *(const LAS f32x4*)(ag + c * 16 + 4 * r4); xg += a[0] * w[4 * r4] + a[1] * w[4 * r4 + 1] + a[2] * w[4 * r4 + 2] + a[3] * w[4 * r4 + 3]; }
;           const float ls = fminf(xg, 0.f) - __logf(1.0f + __expf(-fabsf(xg)));
;           run += ls * (1.0f / 16.0f); bcv[i] = run; }
	ds_read_b128 v[56:59], v55
	ds_read_b128 v[60:63], v55 offset:16
	ds_read_b128 v[64:67], v55 offset:32
	ds_read_b128 v[68:71], v55 offset:48
	s_waitcnt lgkmcnt(3)
	v_mov_b32_e32 v72, v56
	s_waitcnt lgkmcnt(2)
	v_mov_b32_e32 v73, v60
	v_mov_b32_e32 v60, v57
	v_pk_mul_f32 v[56:57], v[12:13], v[60:61]
	v_mov_b32_e32 v60, v58
	v_pk_fma_f32 v[56:57], v[10:11], v[72:73], v[56:57]
	v_mov_b32_e32 v61, v62
	v_pk_fma_f32 v[56:57], v[8:9], v[60:61], v[56:57]
	v_mov_b32_e32 v62, v59
	v_pk_fma_f32 v[56:57], v[20:21], v[62:63], v[56:57]
	s_nop 0
	v_add_f32_e32 v56, v49, v56
	v_add_f32_e32 v60, v56, v57
	s_waitcnt lgkmcnt(0)
	v_mov_b32_e32 v57, v68
	v_mov_b32_e32 v68, v65
	v_mov_b32_e32 v56, v64
	v_pk_mul_f32 v[58:59], v[18:19], v[68:69]
	s_nop 0
	v_pk_fma_f32 v[56:57], v[4:5], v[56:57], v[58:59]
	v_mov_b32_e32 v58, v66
	v_mov_b32_e32 v59, v70
	v_pk_fma_f32 v[56:57], v[14:15], v[58:59], v[56:57]
	v_mov_b32_e32 v70, v67
	v_pk_fma_f32 v[56:57], v[16:17], v[70:71], v[56:57]
	s_nop 0
	v_add_f32_e32 v56, v60, v56
	v_add_f32_e32 v56, v56, v57
	v_mul_f32_e64 v57, |v56|, s44
	v_exp_f32_e32 v57, v57
	v_min_f32_e32 v69, 0, v56
	v_add_f32_e32 v57, 1.0, v57
	v_cmp_gt_f32_e32 vcc, s45, v57
	s_nop 1
	v_cndmask_b32_e64 v58, 0, 32, vcc
	v_ldexp_f32 v57, v57, v58
	v_log_f32_e32 v68, v57
	ds_read_b128 v[56:59], v55 offset:64
	ds_read_b128 v[60:63], v55 offset:80
	v_mul_f32_e32 v64, 0x3f317217, v68
	v_fma_f32 v70, v68, s50, -v64
	s_waitcnt lgkmcnt(0)
	v_mov_b32_e32 v65, v60
	v_mov_b32_e32 v60, v57
	v_mov_b32_e32 v64, v56
	v_pk_mul_f32 v[56:57], v[12:13], v[60:61]
	v_mov_b32_e32 v60, v58
	v_pk_fma_f32 v[56:57], v[10:11], v[64:65], v[56:57]
	v_mov_b32_e32 v61, v62
	v_pk_fma_f32 v[60:61], v[8:9], v[60:61], v[56:57]
	v_mov_b32_e32 v62, v59
	ds_read_b128 v[56:59], v55 offset:96
	ds_read_b128 v[64:67], v55 offset:112
	v_pk_fma_f32 v[60:61], v[20:21], v[62:63], v[60:61]
	v_fmac_f32_e32 v70, 0x3377d1cf, v68
	v_add_f32_e32 v60, v49, v60
	v_add_f32_e32 v62, v60, v61
	s_waitcnt lgkmcnt(0)
	v_mov_b32_e32 v61, v64
	v_mov_b32_e32 v64, v57
	v_mov_b32_e32 v60, v56
	v_pk_mul_f32 v[56:57], v[18:19], v[64:65]
	v_fmac_f32_e32 v70, 0x3f317217, v68
	v_pk_fma_f32 v[56:57], v[4:5], v[60:61], v[56:57]
	v_mov_b32_e32 v60, v58
	v_mov_b32_e32 v61, v66
	v_pk_fma_f32 v[56:57], v[14:15], v[60:61], v[56:57]
	v_mov_b32_e32 v66, v59
	v_pk_fma_f32 v[56:57], v[16:17], v[66:67], v[56:57]
	v_cmp_lt_f32_e64 s[0:1], |v68|, s51
	v_add_f32_e32 v56, v62, v56
	v_add_f32_e32 v57, v56, v57
	v_mul_f32_e64 v56, |v57|, s44
	v_exp_f32_e32 v56, v56
	v_cndmask_b32_e64 v58, v68, v70, s[0:1]
	v_cndmask_b32_e32 v59, 0, v118, vcc
	v_sub_f32_e32 v58, v58, v59
	v_add_f32_e32 v56, 1.0, v56
	v_cmp_gt_f32_e32 vcc, s45, v56
	s_mov_b32 s0, 0x3d800000
	v_min_f32_e32 v57, 0, v57
	v_cndmask_b32_e64 v59, 0, 32, vcc
	v_ldexp_f32 v56, v56, v59
	v_log_f32_e32 v70, v56
	v_sub_f32_e32 v56, v69, v58
	ds_read_b128 v[58:61], v55 offset:128
	ds_read_b128 v[62:65], v55 offset:144
	v_fma_f32 v56, v56, s0, 0
	v_mul_f32_e32 v66, 0x3f317217, v70
	v_fma_f32 v71, v70, s50, -v66
	s_waitcnt lgkmcnt(1)
	v_mov_b32_e32 v66, v58
	s_waitcnt lgkmcnt(0)
	v_mov_b32_e32 v67, v62
	v_mov_b32_e32 v62, v59
	v_pk_mul_f32 v[58:59], v[12:13], v[62:63]
	v_mov_b32_e32 v62, v60
	v_pk_fma_f32 v[58:59], v[10:11], v[66:67], v[58:59]
	v_mov_b32_e32 v63, v64
	v_pk_fma_f32 v[62:63], v[8:9], v[62:63], v[58:59]
	v_mov_b32_e32 v64, v61
	ds_read_b128 v[58:61], v55 offset:160
	ds_read_b128 v[66:69], v55 offset:176
	v_pk_fma_f32 v[62:63], v[20:21], v[64:65], v[62:63]
	v_fmac_f32_e32 v71, 0x3377d1cf, v70
	v_add_f32_e32 v62, v49, v62
	v_add_f32_e32 v64, v62, v63
	s_waitcnt lgkmcnt(0)
	v_mov_b32_e32 v63, v66
	v_mov_b32_e32 v66, v59
	v_mov_b32_e32 v62, v58
	v_pk_mul_f32 v[58:59], v[18:19], v[66:67]
	v_fmac_f32_e32 v71, 0x3f317217, v70
	v_pk_fma_f32 v[58:59], v[4:5], v[62:63], v[58:59]
	v_mov_b32_e32 v62, v60
	v_mov_b32_e32 v63, v68
	v_pk_fma_f32 v[58:59], v[14:15], v[62:63], v[58:59]
	v_mov_b32_e32 v68, v61
	v_pk_fma_f32 v[58:59], v[16:17], v[68:69], v[58:59]
	v_cndmask_b32_e32 v61, 0, v118, vcc
	v_add_f32_e32 v58, v64, v58
	v_add_f32_e32 v58, v58, v59
	v_mul_f32_e64 v59, |v58|, s44
	v_exp_f32_e32 v59, v59
	v_cmp_lt_f32_e64 s[0:1], |v70|, s51
	v_add_f32_e32 v59, 1.0, v59
	v_cmp_gt_f32_e32 vcc, s45, v59
	v_cndmask_b32_e64 v60, v70, v71, s[0:1]
	v_min_f32_e32 v71, 0, v58
	v_cndmask_b32_e64 v62, 0, 32, vcc
	v_ldexp_f32 v59, v59, v62
	v_log_f32_e32 v70, v59
	v_sub_f32_e32 v59, v60, v61
	v_sub_f32_e32 v57, v57, v59
	ds_read_b128 v[58:61], v55 offset:192
	ds_read_b128 v[62:65], v55 offset:208
	v_mul_f32_e32 v66, 0x3f317217, v70
	v_fma_f32 v72, v70, s50, -v66
	v_fmac_f32_e32 v72, 0x3377d1cf, v70
	s_waitcnt lgkmcnt(1)
	v_mov_b32_e32 v66, v58
	s_waitcnt lgkmcnt(0)
	v_mov_b32_e32 v67, v62
	v_mov_b32_e32 v62, v59
	v_pk_mul_f32 v[58:59], v[12:13], v[62:63]
	v_mov_b32_e32 v62, v60
	v_pk_fma_f32 v[58:59], v[10:11], v[66:67], v[58:59]
	v_mov_b32_e32 v63, v64
	v_pk_fma_f32 v[62:63], v[8:9], v[62:63], v[58:59]
	v_mov_b32_e32 v64, v61
	ds_read_b128 v[58:61], v55 offset:224
	ds_read_b128 v[66:69], v55 offset:240
	v_pk_fma_f32 v[62:63], v[20:21], v[64:65], v[62:63]
	v_fmac_f32_e32 v72, 0x3f317217, v70
	v_add_f32_e32 v62, v49, v62
	v_add_f32_e32 v64, v62, v63
	s_waitcnt lgkmcnt(0)
; #define LAS __attribute__((address_space(3)))
; __device__ __forceinline__ void gla_intra_unit(const Params& P, LAS unsigned char* lds, int unit) {
;     ...
;     { const int d = d_, cgp = cgp_;
;       float (&w)[16] = wg_; const float bias = bias_;
;       float bcv[16]; float run = 0.f;
; #pragma unroll
;       for (int i = 0; i < 16; ++i) { const int c = cgp * 16 + i; float xg = bias;
; #pragma unroll
;           for (int r4 = 0; r4 < 4; ++r4) { const f32x4 a = *(const LAS f32x4*)(ag + c * 16 + 4 * r4); xg += a[0] * w[4 * r4] + a[1] * w[4 * r4 + 1] + a[2] * w[4 * r4 + 2] + a[3] * w[4 * r4 + 3]; }
;           const float ls = fminf(xg, 0.f) - __logf(1.0f + __expf(-fabsf(xg)));
;           run += ls * (1.0f / 16.0f); bcv[i] = run; }
	v_mov_b32_e32 v63, v66
	v_mov_b32_e32 v66, v59
	v_mov_b32_e32 v62, v58
	v_pk_mul_f32 v[58:59], v[18:19], v[66:67]
	v_cmp_lt_f32_e64 s[0:1], |v70|, s51
	v_pk_fma_f32 v[58:59], v[4:5], v[62:63], v[58:59]
	v_mov_b32_e32 v62, v60
	v_mov_b32_e32 v63, v68
	v_pk_fma_f32 v[58:59], v[14:15], v[62:63], v[58:59]
	v_mov_b32_e32 v68, v61
	v_pk_fma_f32 v[58:59], v[16:17], v[68:69], v[58:59]
	v_cndmask_b32_e32 v61, 0, v118, vcc
	v_add_f32_e32 v58, v64, v58
	v_add_f32_e32 v59, v58, v59
	v_mul_f32_e64 v58, |v59|, s44
	v_exp_f32_e32 v58, v58
	v_cndmask_b32_e64 v60, v70, v72, s[0:1]
	v_min_f32_e32 v59, 0, v59
	v_add_f32_e32 v58, 1.0, v58
	v_cmp_gt_f32_e32 vcc, s45, v58
	s_nop 1
	v_cndmask_b32_e64 v62, 0, 32, vcc
	v_ldexp_f32 v58, v58, v62
	v_log_f32_e32 v72, v58
	v_sub_f32_e32 v58, v60, v61
	ds_read_b128 v[60:63], v55 offset:256
	ds_read_b128 v[64:67], v55 offset:272
	v_sub_f32_e32 v58, v71, v58
	v_mul_f32_e32 v68, 0x3f317217, v72
	v_fma_f32 v73, v72, s50, -v68
	s_waitcnt lgkmcnt(1)
	v_mov_b32_e32 v68, v60
	s_waitcnt lgkmcnt(0)
	v_mov_b32_e32 v69, v64
	v_mov_b32_e32 v64, v61
	v_pk_mul_f32 v[60:61], v[12:13], v[64:65]
	v_mov_b32_e32 v64, v62
	v_pk_fma_f32 v[60:61], v[10:11], v[68:69], v[60:61]
	v_mov_b32_e32 v65, v66
	v_pk_fma_f32 v[64:65], v[8:9], v[64:65], v[60:61]
	v_mov_b32_e32 v66, v63
	ds_read_b128 v[60:63], v55 offset:288
	ds_read_b128 v[68:71], v55 offset:304
	v_pk_fma_f32 v[64:65], v[20:21], v[66:67], v[64:65]
	v_fmac_f32_e32 v73, 0x3377d1cf, v72
	v_add_f32_e32 v64, v49, v64
	v_add_f32_e32 v66, v64, v65
	s_waitcnt lgkmcnt(0)
	v_mov_b32_e32 v65, v68
	v_mov_b32_e32 v68, v61
	v_mov_b32_e32 v64, v60
	v_pk_mul_f32 v[60:61], v[18:19], v[68:69]
	v_fmac_f32_e32 v73, 0x3f317217, v72
	v_pk_fma_f32 v[60:61], v[4:5], v[64:65], v[60:61]
	v_mov_b32_e32 v64, v62
	v_mov_b32_e32 v65, v70
	v_pk_fma_f32 v[60:61], v[14:15], v[64:65], v[60:61]
	v_mov_b32_e32 v70, v63
	v_pk_fma_f32 v[60:61], v[16:17], v[70:71], v[60:61]
	v_cndmask_b32_e32 v63, 0, v118, vcc
	v_add_f32_e32 v60, v66, v60
	v_add_f32_e32 v60, v60, v61
	v_mul_f32_e64 v61, |v60|, s44
	v_exp_f32_e32 v61, v61
	v_cmp_lt_f32_e64 s[0:1], |v72|, s51
	v_add_f32_e32 v61, 1.0, v61
	v_cmp_gt_f32_e32 vcc, s45, v61
	v_cndmask_b32_e64 v62, v72, v73, s[0:1]
	v_min_f32_e32 v73, 0, v60
	v_cndmask_b32_e64 v64, 0, 32, vcc
	v_ldexp_f32 v61, v61, v64
	v_log_f32_e32 v72, v61
	v_sub_f32_e32 v61, v62, v63
	v_sub_f32_e32 v59, v59, v61
	ds_read_b128 v[60:63], v55 offset:320
	ds_read_b128 v[64:67], v55 offset:336
	v_mul_f32_e32 v68, 0x3f317217, v72
	v_fma_f32 v74, v72, s50, -v68
	v_fmac_f32_e32 v74, 0x3377d1cf, v72
	s_waitcnt lgkmcnt(1)
	v_mov_b32_e32 v68, v60
	s_waitcnt lgkmcnt(0)
	v_mov_b32_e32 v69, v64
	v_mov_b32_e32 v64, v61
	v_pk_mul_f32 v[60:61], v[12:13], v[64:65]
	v_mov_b32_e32 v64, v62
	v_pk_fma_f32 v[60:61], v[10:11], v[68:69], v[60:61]
	v_mov_b32_e32 v65, v66
	v_pk_fma_f32 v[64:65], v[8:9], v[64:65], v[60:61]
	v_mov_b32_e32 v66, v63
	ds_read_b128 v[60:63], v55 offset:352
	ds_read_b128 v[68:71], v55 offset:368
	v_pk_fma_f32 v[64:65], v[20:21], v[66:67], v[64:65]
	v_fmac_f32_e32 v74, 0x3f317217, v72
	v_add_f32_e32 v64, v49, v64
	v_add_f32_e32 v66, v64, v65
	s_waitcnt lgkmcnt(0)
	v_mov_b32_e32 v65, v68
	v_mov_b32_e32 v68, v61
	v_mov_b32_e32 v64, v60
	v_pk_mul_f32 v[60:61], v[18:19], v[68:69]
	v_cmp_lt_f32_e64 s[0:1], |v72|, s51
	v_pk_fma_f32 v[60:61], v[4:5], v[64:65], v[60:61]
	v_mov_b32_e32 v64, v62
	v_mov_b32_e32 v65, v70
	v_pk_fma_f32 v[60:61], v[14:15], v[64:65], v[60:61]
	v_mov_b32_e32 v70, v63
	v_pk_fma_f32 v[60:61], v[16:17], v[70:71], v[60:61]
	v_cndmask_b32_e32 v63, 0, v118, vcc
	v_add_f32_e32 v60, v66, v60
	v_add_f32_e32 v61, v60, v61
	v_mul_f32_e64 v60, |v61|, s44
	v_exp_f32_e32 v60, v60
	v_cndmask_b32_e64 v62, v72, v74, s[0:1]
	v_min_f32_e32 v61, 0, v61
	v_add_f32_e32 v60, 1.0, v60
	v_cmp_gt_f32_e32 vcc, s45, v60
	s_nop 1
	v_cndmask_b32_e64 v64, 0, 32, vcc
	v_ldexp_f32 v60, v60, v64
	v_log_f32_e32 v74, v60
	v_sub_f32_e32 v60, v62, v63
	ds_read_b128 v[62:65], v55 offset:384
	ds_read_b128 v[66:69], v55 offset:400
	v_sub_f32_e32 v60, v73, v60
	v_mul_f32_e32 v70, 0x3f317217, v74
	v_fma_f32 v75, v74, s50, -v70
	s_waitcnt lgkmcnt(1)
	v_mov_b32_e32 v70, v62
	s_waitcnt lgkmcnt(0)
	v_mov_b32_e32 v71, v66
	v_mov_b32_e32 v66, v63
	v_pk_mul_f32 v[62:63], v[12:13], v[66:67]
	v_mov_b32_e32 v66, v64
	v_pk_fma_f32 v[62:63], v[10:11], v[70:71], v[62:63]
	v_mov_b32_e32 v67, v68
	v_pk_fma_f32 v[66:67], v[8:9], v[66:67], v[62:63]
	v_mov_b32_e32 v68, v65
	ds_read_b128 v[62:65], v55 offset:416
	ds_read_b128 v[70:73], v55 offset:432
	v_pk_fma_f32 v[66:67], v[20:21], v[68:69], v[66:67]
	v_fmac_f32_e32 v75, 0x3377d1cf, v74
	v_add_f32_e32 v66, v49, v66
	v_add_f32_e32 v68, v66, v67
	s_waitcnt lgkmcnt(0)
	v_mov_b32_e32 v67, v70
	v_mov_b32_e32 v70, v63
	v_mov_b32_e32 v66, v62
	v_pk_mul_f32 v[62:63], v[18:19], v[70:71]
	v_fmac_f32_e32 v75, 0x3f317217, v74
	v_pk_fma_f32 v[62:63], v[4:5], v[66:67], v[62:63]
	v_mov_b32_e32 v66, v64
	v_mov_b32_e32 v67, v72
	v_pk_fma_f32 v[62:63], v[14:15], v[66:67], v[62:63]
	v_mov_b32_e32 v72, v65
	v_pk_fma_f32 v[62:63], v[16:17], v[72:73], v[62:63]
	v_cndmask_b32_e32 v65, 0, v118, vcc
	v_add_f32_e32 v62, v68, v62
	v_add_f32_e32 v62, v62, v63
	v_mul_f32_e64 v63, |v62|, s44
	v_exp_f32_e32 v63, v63
	v_cmp_lt_f32_e64 s[0:1], |v74|, s51
	v_add_f32_e32 v63, 1.0, v63
	v_cmp_gt_f32_e32 vcc, s45, v63
	v_cndmask_b32_e64 v64, v74, v75, s[0:1]
	v_min_f32_e32 v75, 0, v62
	v_cndmask_b32_e64 v66, 0, 32, vcc
	v_ldexp_f32 v63, v63, v66
	v_log_f32_e32 v74, v63
	v_sub_f32_e32 v63, v64, v65
	v_sub_f32_e32 v61, v61, v63
	ds_read_b128 v[62:65], v55 offset:448
	ds_read_b128 v[66:69], v55 offset:464
	v_mul_f32_e32 v70, 0x3f317217, v74
	v_fma_f32 v76, v74, s50, -v70
	v_fmac_f32_e32 v76, 0x3377d1cf, v74
	s_waitcnt lgkmcnt(1)
; #define LAS __attribute__((address_space(3)))
; __device__ __forceinline__ void gla_intra_unit(const Params& P, LAS unsigned char* lds, int unit) {
;     ...
;     { const int d = d_, cgp = cgp_;
;       float (&w)[16] = wg_; const float bias = bias_;
;       float bcv[16]; float run = 0.f;
; #pragma unroll
;       for (int i = 0; i < 16; ++i) { const int c = cgp * 16 + i; float xg = bias;
; #pragma unroll
;           for (int r4 = 0; r4 < 4; ++r4) { const f32x4 a = *(const LAS f32x4*)(ag + c * 16 + 4 * r4); xg += a[0] * w[4 * r4] + a[1] * w[4 * r4 + 1] + a[2] * w[4 * r4 + 2] + a[3] * w[4 * r4 + 3]; }
;           const float ls = fminf(xg, 0.f) - __logf(1.0f + __expf(-fabsf(xg)));
;           run += ls * (1.0f / 16.0f); bcv[i] = run; }
	v_mov_b32_e32 v70, v62
	s_waitcnt lgkmcnt(0)
	v_mov_b32_e32 v71, v66
	v_mov_b32_e32 v66, v63
	v_pk_mul_f32 v[62:63], v[12:13], v[66:67]
	v_mov_b32_e32 v66, v64
	v_pk_fma_f32 v[62:63], v[10:11], v[70:71], v[62:63]
	v_mov_b32_e32 v67, v68
	v_pk_fma_f32 v[66:67], v[8:9], v[66:67], v[62:63]
	v_mov_b32_e32 v68, v65
	ds_read_b128 v[62:65], v55 offset:480
	ds_read_b128 v[70:73], v55 offset:496
	v_pk_fma_f32 v[66:67], v[20:21], v[68:69], v[66:67]
	v_fmac_f32_e32 v76, 0x3f317217, v74
	v_add_f32_e32 v66, v49, v66
	v_add_f32_e32 v68, v66, v67
	s_waitcnt lgkmcnt(0)
	v_mov_b32_e32 v67, v70
	v_mov_b32_e32 v70, v63
	v_mov_b32_e32 v66, v62
	v_pk_mul_f32 v[62:63], v[18:19], v[70:71]
	v_cmp_lt_f32_e64 s[0:1], |v74|, s51
	v_pk_fma_f32 v[62:63], v[4:5], v[66:67], v[62:63]
	v_mov_b32_e32 v66, v64
	v_mov_b32_e32 v67, v72
	v_pk_fma_f32 v[62:63], v[14:15], v[66:67], v[62:63]
	v_mov_b32_e32 v72, v65
	v_pk_fma_f32 v[62:63], v[16:17], v[72:73], v[62:63]
	v_cndmask_b32_e32 v65, 0, v118, vcc
	v_add_f32_e32 v62, v68, v62
	v_add_f32_e32 v63, v62, v63
	v_mul_f32_e64 v62, |v63|, s44
	v_exp_f32_e32 v62, v62
	v_cndmask_b32_e64 v64, v74, v76, s[0:1]
	v_min_f32_e32 v63, 0, v63
	v_add_f32_e32 v62, 1.0, v62
	v_cmp_gt_f32_e32 vcc, s45, v62
	s_nop 1
	v_cndmask_b32_e64 v66, 0, 32, vcc
	v_ldexp_f32 v62, v62, v66
	v_log_f32_e32 v76, v62
	v_sub_f32_e32 v62, v64, v65
	ds_read_b128 v[64:67], v55 offset:512
	ds_read_b128 v[68:71], v55 offset:528
	v_sub_f32_e32 v62, v75, v62
	v_mul_f32_e32 v72, 0x3f317217, v76
	v_fma_f32 v77, v76, s50, -v72
	s_waitcnt lgkmcnt(1)
	v_mov_b32_e32 v72, v64
	s_waitcnt lgkmcnt(0)
	v_mov_b32_e32 v73, v68
	v_mov_b32_e32 v68, v65
	v_pk_mul_f32 v[64:65], v[12:13], v[68:69]
	v_mov_b32_e32 v68, v66
	v_pk_fma_f32 v[64:65], v[10:11], v[72:73], v[64:65]
	v_mov_b32_e32 v69, v70
	v_pk_fma_f32 v[68:69], v[8:9], v[68:69], v[64:65]
	v_mov_b32_e32 v70, v67
	ds_read_b128 v[64:67], v55 offset:544
	ds_read_b128 v[72:75], v55 offset:560
	v_pk_fma_f32 v[68:69], v[20:21], v[70:71], v[68:69]
	v_fmac_f32_e32 v77, 0x3377d1cf, v76
	v_add_f32_e32 v68, v49, v68
	v_add_f32_e32 v70, v68, v69
	s_waitcnt lgkmcnt(0)
	v_mov_b32_e32 v69, v72
	v_mov_b32_e32 v72, v65
	v_mov_b32_e32 v68, v64
	v_pk_mul_f32 v[64:65], v[18:19], v[72:73]
	v_fmac_f32_e32 v77, 0x3f317217, v76
	v_pk_fma_f32 v[64:65], v[4:5], v[68:69], v[64:65]
	v_mov_b32_e32 v68, v66
	v_mov_b32_e32 v69, v74
	v_pk_fma_f32 v[64:65], v[14:15], v[68:69], v[64:65]
	v_mov_b32_e32 v74, v67
	v_pk_fma_f32 v[64:65], v[16:17], v[74:75], v[64:65]
	v_cndmask_b32_e32 v67, 0, v118, vcc
	v_add_f32_e32 v64, v70, v64
	v_add_f32_e32 v64, v64, v65
	v_mul_f32_e64 v65, |v64|, s44
	v_exp_f32_e32 v65, v65
	v_cmp_lt_f32_e64 s[0:1], |v76|, s51
	v_add_f32_e32 v65, 1.0, v65
	v_cmp_gt_f32_e32 vcc, s45, v65
	v_cndmask_b32_e64 v66, v76, v77, s[0:1]
	v_min_f32_e32 v77, 0, v64
	v_cndmask_b32_e64 v68, 0, 32, vcc
	v_ldexp_f32 v65, v65, v68
	v_log_f32_e32 v76, v65
	v_sub_f32_e32 v65, v66, v67
	v_sub_f32_e32 v63, v63, v65
	ds_read_b128 v[64:67], v55 offset:576
	ds_read_b128 v[68:71], v55 offset:592
	v_mul_f32_e32 v72, 0x3f317217, v76
	v_fma_f32 v78, v76, s50, -v72
	v_fmac_f32_e32 v78, 0x3377d1cf, v76
	s_waitcnt lgkmcnt(1)
	v_mov_b32_e32 v72, v64
	s_waitcnt lgkmcnt(0)
	v_mov_b32_e32 v73, v68
	v_mov_b32_e32 v68, v65
	v_pk_mul_f32 v[64:65], v[12:13], v[68:69]
	v_mov_b32_e32 v68, v66
	v_pk_fma_f32 v[64:65], v[10:11], v[72:73], v[64:65]
	v_mov_b32_e32 v69, v70
	v_pk_fma_f32 v[68:69], v[8:9], v[68:69], v[64:65]
	v_mov_b32_e32 v70, v67
	ds_read_b128 v[64:67], v55 offset:608
	ds_read_b128 v[72:75], v55 offset:624
	v_pk_fma_f32 v[68:69], v[20:21], v[70:71], v[68:69]
	v_fmac_f32_e32 v78, 0x3f317217, v76
	v_add_f32_e32 v68, v49, v68
	v_add_f32_e32 v70, v68, v69
	s_waitcnt lgkmcnt(0)
	v_mov_b32_e32 v69, v72
	v_mov_b32_e32 v72, v65
	v_mov_b32_e32 v68, v64
	v_pk_mul_f32 v[64:65], v[18:19], v[72:73]
	v_cmp_lt_f32_e64 s[0:1], |v76|, s51
	v_pk_fma_f32 v[64:65], v[4:5], v[68:69], v[64:65]
	v_mov_b32_e32 v68, v66
	v_mov_b32_e32 v69, v74
	v_pk_fma_f32 v[64:65], v[14:15], v[68:69], v[64:65]
	v_mov_b32_e32 v74, v67
	v_pk_fma_f32 v[64:65], v[16:17], v[74:75], v[64:65]
	v_cndmask_b32_e32 v67, 0, v118, vcc
	v_add_f32_e32 v64, v70, v64
	v_add_f32_e32 v64, v64, v65
	v_mul_f32_e64 v65, |v64|, s44
	v_exp_f32_e32 v65, v65
	v_cndmask_b32_e64 v66, v76, v78, s[0:1]
	v_min_f32_e32 v78, 0, v64
	v_add_f32_e32 v65, 1.0, v65
	v_cmp_gt_f32_e32 vcc, s45, v65
	s_nop 1
	v_cndmask_b32_e64 v68, 0, 32, vcc
	v_ldexp_f32 v65, v65, v68
	v_log_f32_e32 v76, v65
	v_sub_f32_e32 v65, v66, v67
	v_sub_f32_e32 v77, v77, v65
	ds_read_b128 v[64:67], v55 offset:640
	ds_read_b128 v[68:71], v55 offset:656
	v_mul_f32_e32 v72, 0x3f317217, v76
	v_fma_f32 v79, v76, s50, -v72
	v_fmac_f32_e32 v79, 0x3377d1cf, v76
	s_waitcnt lgkmcnt(1)
	v_mov_b32_e32 v72, v64
	s_waitcnt lgkmcnt(0)
	v_mov_b32_e32 v73, v68
	v_mov_b32_e32 v68, v65
	v_pk_mul_f32 v[64:65], v[12:13], v[68:69]
	v_mov_b32_e32 v68, v66
	v_pk_fma_f32 v[64:65], v[10:11], v[72:73], v[64:65]
	v_mov_b32_e32 v69, v70
	v_pk_fma_f32 v[68:69], v[8:9], v[68:69], v[64:65]
	v_mov_b32_e32 v70, v67
	ds_read_b128 v[64:67], v55 offset:672
	ds_read_b128 v[72:75], v55 offset:688
	v_pk_fma_f32 v[68:69], v[20:21], v[70:71], v[68:69]
	v_fmac_f32_e32 v79, 0x3f317217, v76
	v_add_f32_e32 v68, v49, v68
	v_add_f32_e32 v70, v68, v69
	s_waitcnt lgkmcnt(0)
; #define LAS __attribute__((address_space(3)))
; __device__ __forceinline__ void gla_intra_unit(const Params& P, LAS unsigned char* lds, int unit) {
;     ...
;     { const int d = d_, cgp = cgp_;
;       float (&w)[16] = wg_; const float bias = bias_;
;       float bcv[16]; float run = 0.f;
; #pragma unroll
;       for (int i = 0; i < 16; ++i) { const int c = cgp * 16 + i; float xg = bias;
; #pragma unroll
;           for (int r4 = 0; r4 < 4; ++r4) { const f32x4 a = *(const LAS f32x4*)(ag + c * 16 + 4 * r4); xg += a[0] * w[4 * r4] + a[1] * w[4 * r4 + 1] + a[2] * w[4 * r4 + 2] + a[3] * w[4 * r4 + 3]; }
;           const float ls = fminf(xg, 0.f) - __logf(1.0f + __expf(-fabsf(xg)));
;           run += ls * (1.0f / 16.0f); bcv[i] = run; }
	v_mov_b32_e32 v69, v72
	v_mov_b32_e32 v72, v65
	v_mov_b32_e32 v68, v64
	v_pk_mul_f32 v[64:65], v[18:19], v[72:73]
	v_cmp_lt_f32_e64 s[0:1], |v76|, s51
	v_pk_fma_f32 v[64:65], v[4:5], v[68:69], v[64:65]
	v_mov_b32_e32 v68, v66
	v_mov_b32_e32 v69, v74
	v_pk_fma_f32 v[64:65], v[14:15], v[68:69], v[64:65]
	v_mov_b32_e32 v74, v67
	v_pk_fma_f32 v[64:65], v[16:17], v[74:75], v[64:65]
	v_cndmask_b32_e32 v67, 0, v118, vcc
	v_add_f32_e32 v64, v70, v64
	v_add_f32_e32 v64, v64, v65
	v_mul_f32_e64 v65, |v64|, s44
	v_exp_f32_e32 v65, v65
	v_cndmask_b32_e64 v66, v76, v79, s[0:1]
	v_min_f32_e32 v79, 0, v64
	v_add_f32_e32 v65, 1.0, v65
	v_cmp_gt_f32_e32 vcc, s45, v65
	s_nop 1
	v_cndmask_b32_e64 v68, 0, 32, vcc
	v_ldexp_f32 v65, v65, v68
	v_log_f32_e32 v76, v65
	v_sub_f32_e32 v65, v66, v67
	v_sub_f32_e32 v78, v78, v65
	ds_read_b128 v[64:67], v55 offset:704
	ds_read_b128 v[68:71], v55 offset:720
	v_mul_f32_e32 v72, 0x3f317217, v76
	v_fma_f32 v80, v76, s50, -v72
	v_fmac_f32_e32 v80, 0x3377d1cf, v76
	s_waitcnt lgkmcnt(1)
	v_mov_b32_e32 v72, v64
	s_waitcnt lgkmcnt(0)
	v_mov_b32_e32 v73, v68
	v_mov_b32_e32 v68, v65
	v_pk_mul_f32 v[64:65], v[12:13], v[68:69]
	v_mov_b32_e32 v68, v66
	v_pk_fma_f32 v[64:65], v[10:11], v[72:73], v[64:65]
	v_mov_b32_e32 v69, v70
	v_pk_fma_f32 v[68:69], v[8:9], v[68:69], v[64:65]
	v_mov_b32_e32 v70, v67
	ds_read_b128 v[64:67], v55 offset:736
	ds_read_b128 v[72:75], v55 offset:752
	v_pk_fma_f32 v[68:69], v[20:21], v[70:71], v[68:69]
	v_fmac_f32_e32 v80, 0x3f317217, v76
	v_add_f32_e32 v68, v49, v68
	v_add_f32_e32 v70, v68, v69
	s_waitcnt lgkmcnt(0)
	v_mov_b32_e32 v69, v72
	v_mov_b32_e32 v72, v65
	v_mov_b32_e32 v68, v64
	v_pk_mul_f32 v[64:65], v[18:19], v[72:73]
	v_cmp_lt_f32_e64 s[0:1], |v76|, s51
	v_pk_fma_f32 v[64:65], v[4:5], v[68:69], v[64:65]
	v_mov_b32_e32 v68, v66
	v_mov_b32_e32 v69, v74
	v_pk_fma_f32 v[64:65], v[14:15], v[68:69], v[64:65]
	v_mov_b32_e32 v74, v67
	v_pk_fma_f32 v[64:65], v[16:17], v[74:75], v[64:65]
	v_cndmask_b32_e32 v67, 0, v118, vcc
	v_add_f32_e32 v64, v70, v64
	v_add_f32_e32 v64, v64, v65
	v_mul_f32_e64 v65, |v64|, s44
	v_exp_f32_e32 v65, v65
	v_cndmask_b32_e64 v66, v76, v80, s[0:1]
	v_min_f32_e32 v80, 0, v64
	v_add_f32_e32 v65, 1.0, v65
	v_cmp_gt_f32_e32 vcc, s45, v65
	s_nop 1
	v_cndmask_b32_e64 v68, 0, 32, vcc
	v_ldexp_f32 v65, v65, v68
	v_log_f32_e32 v76, v65
	v_sub_f32_e32 v65, v66, v67
	v_sub_f32_e32 v79, v79, v65
	ds_read_b128 v[64:67], v55 offset:768
	ds_read_b128 v[68:71], v55 offset:784
	v_mul_f32_e32 v72, 0x3f317217, v76
	v_fma_f32 v81, v76, s50, -v72
	v_fmac_f32_e32 v81, 0x3377d1cf, v76
	s_waitcnt lgkmcnt(1)
	v_mov_b32_e32 v72, v64
	s_waitcnt lgkmcnt(0)
	v_mov_b32_e32 v73, v68
	v_mov_b32_e32 v68, v65
	v_pk_mul_f32 v[64:65], v[12:13], v[68:69]
	v_mov_b32_e32 v68, v66
	v_pk_fma_f32 v[64:65], v[10:11], v[72:73], v[64:65]
	v_mov_b32_e32 v69, v70
	v_pk_fma_f32 v[68:69], v[8:9], v[68:69], v[64:65]
	v_mov_b32_e32 v70, v67
	ds_read_b128 v[64:67], v55 offset:800
	ds_read_b128 v[72:75], v55 offset:816
	v_pk_fma_f32 v[68:69], v[20:21], v[70:71], v[68:69]
	v_fmac_f32_e32 v81, 0x3f317217, v76
	v_add_f32_e32 v68, v49, v68
	v_add_f32_e32 v70, v68, v69
	s_waitcnt lgkmcnt(0)
	v_mov_b32_e32 v69, v72
	v_mov_b32_e32 v72, v65
	v_mov_b32_e32 v68, v64
	v_pk_mul_f32 v[64:65], v[18:19], v[72:73]
	v_cmp_lt_f32_e64 s[0:1], |v76|, s51
	v_pk_fma_f32 v[64:65], v[4:5], v[68:69], v[64:65]
	v_mov_b32_e32 v68, v66
	v_mov_b32_e32 v69, v74
	v_pk_fma_f32 v[64:65], v[14:15], v[68:69], v[64:65]
	v_mov_b32_e32 v74, v67
	v_pk_fma_f32 v[64:65], v[16:17], v[74:75], v[64:65]
	v_cndmask_b32_e32 v67, 0, v118, vcc
	v_add_f32_e32 v64, v70, v64
	v_add_f32_e32 v64, v64, v65
	v_mul_f32_e64 v65, |v64|, s44
	v_exp_f32_e32 v65, v65
	v_cndmask_b32_e64 v66, v76, v81, s[0:1]
	v_min_f32_e32 v81, 0, v64
	v_add_f32_e32 v65, 1.0, v65
	v_cmp_gt_f32_e32 vcc, s45, v65
	s_nop 1
	v_cndmask_b32_e64 v68, 0, 32, vcc
	v_ldexp_f32 v65, v65, v68
	v_log_f32_e32 v76, v65
	v_sub_f32_e32 v65, v66, v67
	v_sub_f32_e32 v80, v80, v65
	ds_read_b128 v[64:67], v55 offset:832
	ds_read_b128 v[68:71], v55 offset:848
	v_mul_f32_e32 v72, 0x3f317217, v76
	v_fma_f32 v82, v76, s50, -v72
	v_fmac_f32_e32 v82, 0x3377d1cf, v76
	s_waitcnt lgkmcnt(1)
	v_mov_b32_e32 v72, v64
	s_waitcnt lgkmcnt(0)
	v_mov_b32_e32 v73, v68
	v_mov_b32_e32 v68, v65
	v_pk_mul_f32 v[64:65], v[12:13], v[68:69]
	v_mov_b32_e32 v68, v66
	v_pk_fma_f32 v[64:65], v[10:11], v[72:73], v[64:65]
	v_mov_b32_e32 v69, v70
	v_pk_fma_f32 v[68:69], v[8:9], v[68:69], v[64:65]
	v_mov_b32_e32 v70, v67
	ds_read_b128 v[64:67], v55 offset:864
	ds_read_b128 v[72:75], v55 offset:880
	v_pk_fma_f32 v[68:69], v[20:21], v[70:71], v[68:69]
	v_fmac_f32_e32 v82, 0x3f317217, v76
	v_add_f32_e32 v68, v49, v68
	v_add_f32_e32 v70, v68, v69
	s_waitcnt lgkmcnt(0)
	v_mov_b32_e32 v69, v72
	v_mov_b32_e32 v72, v65
	v_mov_b32_e32 v68, v64
	v_pk_mul_f32 v[64:65], v[18:19], v[72:73]
	v_cmp_lt_f32_e64 s[0:1], |v76|, s51
	v_pk_fma_f32 v[64:65], v[4:5], v[68:69], v[64:65]
	v_mov_b32_e32 v68, v66
	v_mov_b32_e32 v69, v74
	v_pk_fma_f32 v[64:65], v[14:15], v[68:69], v[64:65]
	v_mov_b32_e32 v74, v67
	v_pk_fma_f32 v[64:65], v[16:17], v[74:75], v[64:65]
	v_cndmask_b32_e32 v67, 0, v118, vcc
	v_add_f32_e32 v64, v70, v64
	v_add_f32_e32 v64, v64, v65
	v_mul_f32_e64 v65, |v64|, s44
	v_exp_f32_e32 v65, v65
	v_cndmask_b32_e64 v66, v76, v82, s[0:1]
	v_min_f32_e32 v82, 0, v64
	v_add_f32_e32 v65, 1.0, v65
	v_cmp_gt_f32_e32 vcc, s45, v65
	s_nop 1
	v_cndmask_b32_e64 v68, 0, 32, vcc
	v_ldexp_f32 v65, v65, v68
	v_log_f32_e32 v76, v65
	v_sub_f32_e32 v65, v66, v67
	v_sub_f32_e32 v81, v81, v65
	ds_read_b128 v[64:67], v55 offset:896
	ds_read_b128 v[68:71], v55 offset:912
	v_mul_f32_e32 v72, 0x3f317217, v76
	v_fma_f32 v83, v76, s50, -v72
	v_fmac_f32_e32 v83, 0x3377d1cf, v76
	s_waitcnt lgkmcnt(1)
; #define LAS __attribute__((address_space(3)))
; __device__ __forceinline__ float bf2f(unsigned short u) { return __uint_as_float((unsigned)u << 16); }
; __device__ __forceinline__ unsigned short f2bf(float f) { unsigned u = __float_as_uint(f); return (unsigned short)((u + 0x7fffu + ((u >> 16) & 1u)) >> 16); }
; __device__ __forceinline__ void gla_intra_unit(const Params& P, LAS unsigned char* lds, int unit) {
;     ...
;       for (int i = 0; i < 16; ++i) { const int c = cgp * 16 + i; float xg = bias;
; #pragma unroll
;           for (int r4 = 0; r4 < 4; ++r4) { const f32x4 a = *(const LAS f32x4*)(ag + c * 16 + 4 * r4); xg += a[0] * w[4 * r4] + a[1] * w[4 * r4 + 1] + a[2] * w[4 * r4 + 2] + a[3] * w[4 * r4 + 3]; }
;           const float ls = fminf(xg, 0.f) - __logf(1.0f + __expf(-fabsf(xg)));
;           run += ls * (1.0f / 16.0f); bcv[i] = run; }
;       seg[cgp * 128 + d] = run;
;       __syncthreads();
;       float off = 0.f, tot = 0.f;
; #pragma unroll
;       for (int g2 = 0; g2 < 4; ++g2) { const float sv = seg[g2 * 128 + d]; tot += sv; if (g2 < cgp) off += sv; }
;       float kd_prev = 0.f;
; #pragma unroll
;       for (int i = 0; i < 16; ++i) { const int c = cgp * 16 + i; const float bc = bcv[i] + off;
;           const float q = bf2f(qraw_[i]), k = bf2f(kraw_[i]);
;           const bf16_t qv = f2bf(q * 0.08838834764831845f * __expf(bc));
;           qd[c * 136 + d] = qv; ki[c * 136 + d] = f2bf(k * __expf(-bc));
	v_mov_b32_e32 v72, v64
	s_waitcnt lgkmcnt(0)
	v_mov_b32_e32 v73, v68
	v_mov_b32_e32 v68, v65
	v_pk_mul_f32 v[64:65], v[12:13], v[68:69]
	v_mov_b32_e32 v68, v66
	v_pk_fma_f32 v[64:65], v[10:11], v[72:73], v[64:65]
	v_mov_b32_e32 v69, v70
	v_pk_fma_f32 v[68:69], v[8:9], v[68:69], v[64:65]
	v_mov_b32_e32 v70, v67
	ds_read_b128 v[64:67], v55 offset:928
	ds_read_b128 v[72:75], v55 offset:944
	v_pk_fma_f32 v[68:69], v[20:21], v[70:71], v[68:69]
	v_fmac_f32_e32 v83, 0x3f317217, v76
	v_add_f32_e32 v68, v49, v68
	v_add_f32_e32 v70, v68, v69
	s_waitcnt lgkmcnt(0)
	v_mov_b32_e32 v69, v72
	v_mov_b32_e32 v72, v65
	v_mov_b32_e32 v68, v64
	v_pk_mul_f32 v[64:65], v[18:19], v[72:73]
	v_cmp_lt_f32_e64 s[0:1], |v76|, s51
	v_pk_fma_f32 v[64:65], v[4:5], v[68:69], v[64:65]
	v_mov_b32_e32 v68, v66
	v_mov_b32_e32 v69, v74
	v_pk_fma_f32 v[64:65], v[14:15], v[68:69], v[64:65]
	v_mov_b32_e32 v74, v67
	v_pk_fma_f32 v[64:65], v[16:17], v[74:75], v[64:65]
	v_cndmask_b32_e32 v67, 0, v118, vcc
	v_add_f32_e32 v64, v70, v64
	v_add_f32_e32 v64, v64, v65
	v_mul_f32_e64 v65, |v64|, s44
	v_exp_f32_e32 v65, v65
	v_cndmask_b32_e64 v66, v76, v83, s[0:1]
	v_min_f32_e32 v76, 0, v64
	v_add_f32_e32 v65, 1.0, v65
	v_cmp_gt_f32_e32 vcc, s45, v65
	s_nop 1
	v_cndmask_b32_e64 v68, 0, 32, vcc
	v_ldexp_f32 v65, v65, v68
	v_log_f32_e32 v74, v65
	v_sub_f32_e32 v65, v66, v67
	v_sub_f32_e32 v75, v82, v65
	ds_read_b128 v[64:67], v55 offset:960
	ds_read_b128 v[68:71], v55 offset:976
	v_mul_f32_e32 v72, 0x3f317217, v74
	v_fma_f32 v82, v74, s50, -v72
	v_fmac_f32_e32 v82, 0x3377d1cf, v74
	s_waitcnt lgkmcnt(1)
	v_mov_b32_e32 v72, v64
	s_waitcnt lgkmcnt(0)
	v_mov_b32_e32 v73, v68
	v_mov_b32_e32 v68, v65
	v_pk_mul_f32 v[12:13], v[12:13], v[68:69]
	v_fmac_f32_e32 v82, 0x3f317217, v74
	v_pk_fma_f32 v[10:11], v[10:11], v[72:73], v[12:13]
	v_mov_b32_e32 v12, v66
	v_mov_b32_e32 v13, v70
	v_pk_fma_f32 v[12:13], v[8:9], v[12:13], v[10:11]
	v_mov_b32_e32 v70, v67
	ds_read_b128 v[8:11], v55 offset:992
	ds_read_b128 v[64:67], v55 offset:1008
	v_pk_fma_f32 v[12:13], v[20:21], v[70:71], v[12:13]
	v_cmp_lt_f32_e64 s[0:1], |v74|, s51
	v_add_f32_e32 v12, v49, v12
	v_add_f32_e32 v20, v12, v13
	s_waitcnt lgkmcnt(0)
	v_mov_b32_e32 v13, v64
	v_mov_b32_e32 v64, v9
	v_mov_b32_e32 v12, v8
	v_pk_mul_f32 v[8:9], v[18:19], v[64:65]
	s_nop 0
	v_pk_fma_f32 v[4:5], v[4:5], v[12:13], v[8:9]
	v_mov_b32_e32 v8, v10
	v_mov_b32_e32 v9, v66
	v_pk_fma_f32 v[4:5], v[14:15], v[8:9], v[4:5]
	v_mov_b32_e32 v66, v11
	v_pk_fma_f32 v[4:5], v[16:17], v[66:67], v[4:5]
	v_cndmask_b32_e32 v9, 0, v118, vcc
	v_add_f32_e32 v4, v20, v4
	v_add_f32_e32 v4, v4, v5
	v_mul_f32_e64 v5, |v4|, s44
	v_exp_f32_e32 v5, v5
	v_cndmask_b32_e64 v8, v74, v82, s[0:1]
	v_sub_f32_e32 v8, v8, v9
	v_min_f32_e32 v4, 0, v4
	v_add_f32_e32 v5, 1.0, v5
	v_cmp_gt_f32_e32 vcc, s45, v5
	v_add_u32_e32 v14, 0, v28
	v_lshlrev_b32_e32 v12, 16, v52
	v_cndmask_b32_e64 v10, 0, 32, vcc
	v_ldexp_f32 v5, v5, v10
	v_log_f32_e32 v5, v5
	v_sub_f32_e32 v8, v76, v8
	v_mul_u32_u24_e32 v15, 0x8c, v2
	v_mul_f32_e32 v9, 0x3f317217, v5
	v_fma_f32 v9, v5, s50, -v9
	v_fmac_f32_e32 v9, 0x3377d1cf, v5
	v_fmac_f32_e32 v9, 0x3f317217, v5
	v_cmp_lt_f32_e64 s[0:1], |v5|, s51
	s_nop 1
	v_cndmask_b32_e64 v5, v5, v9, s[0:1]
	v_cndmask_b32_e32 v9, 0, v118, vcc
	v_sub_f32_e32 v5, v5, v9
	v_sub_f32_e32 v4, v4, v5
	v_fmamk_f32 v5, v57, 0x3d800000, v56
	v_fmamk_f32 v16, v58, 0x3d800000, v5
	v_fmamk_f32 v17, v59, 0x3d800000, v16
	v_fmamk_f32 v18, v60, 0x3d800000, v17
	v_fmamk_f32 v19, v61, 0x3d800000, v18
	v_fmamk_f32 v20, v62, 0x3d800000, v19
	v_fmamk_f32 v21, v63, 0x3d800000, v20
	v_fmamk_f32 v28, v77, 0x3d800000, v21
	v_fmamk_f32 v49, v78, 0x3d800000, v28
	v_fmamk_f32 v52, v79, 0x3d800000, v49
	v_fmamk_f32 v55, v80, 0x3d800000, v52
	v_fmamk_f32 v57, v81, 0x3d800000, v55
	v_fmamk_f32 v58, v75, 0x3d800000, v57
	v_fmamk_f32 v59, v8, 0x3d800000, v58
	v_lshl_add_u32 v9, v0, 2, 0
	v_fmamk_f32 v60, v4, 0x3d800000, v59
	ds_write_b32 v9, v60 offset:4096
	s_waitcnt lgkmcnt(0)
	s_barrier
	ds_read2st64_b32 v[10:11], v14 offset0:16 offset1:18
	s_movk_i32 s0, 0x880
	v_mul_lo_u32 v4, v24, s0
	v_mul_f32_e32 v8, 0x3db504f3, v12
	v_or_b32_e32 v4, v4, v2
	ds_read2st64_b32 v[12:13], v14 offset0:20 offset1:22
	v_lshl_add_u32 v61, v4, 1, 0
	s_waitcnt lgkmcnt(1)
	v_add_f32_e32 v4, 0, v10
	v_cmp_lt_i32_e32 vcc, 0, v24
	v_or_b32_e32 v62, 1, v6
	s_movk_i32 s0, 0x88
	v_cndmask_b32_e32 v9, 0, v4, vcc
	v_add_f32_e32 v10, v11, v9
	v_cmp_lt_i32_e32 vcc, 1, v24
	v_add_f32_e32 v4, v4, v11
	s_waitcnt lgkmcnt(0)
; #define LAS __attribute__((address_space(3)))
; __device__ __forceinline__ float bf2f(unsigned short u) { return __uint_as_float((unsigned)u << 16); }
; __device__ __forceinline__ unsigned short f2bf(float f) { unsigned u = __float_as_uint(f); return (unsigned short)((u + 0x7fffu + ((u >> 16) & 1u)) >> 16); }
; __device__ __forceinline__ unsigned pk2(float lo, float hi) { return pg8::cvtpk(lo, hi); }
; __device__ __forceinline__ void gla_intra_unit(const Params& P, LAS unsigned char* lds, int unit) {
;     ...
;       float kd_prev = 0.f;
; #pragma unroll
;       for (int i = 0; i < 16; ++i) { const int c = cgp * 16 + i; const float bc = bcv[i] + off;
;           const float q = bf2f(qraw_[i]), k = bf2f(kraw_[i]);
;           const bf16_t qv = f2bf(q * 0.08838834764831845f * __expf(bc));
;           qd[c * 136 + d] = qv; ki[c * 136 + d] = f2bf(k * __expf(-bc));
;           const float kdv = k * __expf(tot - bc);
;           if (i & 1) *(LAS unsigned*)(kdT + d * 72 + c - 1) = pk2(kd_prev, kdv); else kd_prev = kdv; }
	v_add_f32_e32 v4, v4, v12
	v_cndmask_b32_e32 v9, v9, v10, vcc
	v_add_f32_e32 v10, v12, v9
	v_cmp_lt_i32_e32 vcc, 2, v24
	s_nop 1
	v_cndmask_b32_e32 v9, v9, v10, vcc
	v_add_f32_e32 v10, v13, v9
	v_cmp_lt_i32_e32 vcc, 3, v24
	s_nop 1
	v_cndmask_b32_e32 v9, v9, v10, vcc
	v_add_f32_e32 v10, v56, v9
	v_mul_f32_e32 v56, 0x3fb8aa3b, v10
	v_exp_f32_e32 v56, v56
	s_nop 0
	v_mul_f32_e32 v8, v8, v56
	v_bfe_u32 v11, v8, 16, 1
	v_add3_u32 v8, v8, v11, s62
	ds_write_b16_d16_hi v61, v8 offset:8192
	v_mul_f32_e32 v8, 0xbfb8aa3b, v10
	v_exp_f32_e32 v56, v8
	v_mov_b32_e32 v8, v13
	v_pk_add_f32 v[4:5], v[4:5], v[8:9]
	v_mad_u64_u32 v[12:13], s[0:1], v62, s0, v[2:3]
	v_sub_f32_e32 v8, v4, v10
	v_mul_f32_e32 v10, 0x3fb8aa3b, v5
	v_exp_f32_e32 v11, v10
	v_mul_f32_e32 v8, 0x3fb8aa3b, v8
	v_exp_f32_e32 v10, v8
	v_lshlrev_b32_e32 v8, 16, v43
	v_mul_f32_e32 v8, 0x3db504f3, v8
	v_mul_f32_e32 v8, v8, v11
	v_bfe_u32 v11, v8, 16, 1
	v_add3_u32 v8, v8, v11, s62
	v_mul_f32_e32 v11, 0xbfb8aa3b, v5
	v_sub_f32_e32 v5, v4, v5
	v_lshl_add_u32 v2, v12, 1, 0
	v_exp_f32_e32 v43, v11
	v_mul_f32_e32 v5, 0x3fb8aa3b, v5
	v_lshlrev_b32_e32 v12, 16, v41
	v_exp_f32_e32 v11, v5
	v_mul_f32_e32 v5, v56, v12
	v_lshlrev_b32_e32 v13, 16, v40
	v_bfe_u32 v40, v5, 16, 1
	v_add3_u32 v5, v5, v40, s62
	ds_write_b16_d16_hi v61, v5 offset:25600
	ds_write_b16_d16_hi v2, v8 offset:8192
	v_mul_f32_e32 v5, v43, v13
	v_bfe_u32 v8, v5, 16, 1
	v_add3_u32 v5, v5, v8, s62
	v_pk_mul_f32 v[10:11], v[10:11], v[12:13]
	v_add_f32_e32 v8, v16, v9
	v_cvt_pk_bf16_f32 v10, v10, v11
	v_mul_f32_e32 v11, 0x3fb8aa3b, v8
	v_exp_f32_e32 v11, v11
	v_lshlrev_b32_e32 v12, 16, v36
	v_mul_f32_e32 v12, 0x3db504f3, v12
	v_add_f32_e32 v13, v17, v9
	v_mul_f32_e32 v11, v12, v11
	v_bfe_u32 v12, v11, 16, 1
	ds_write_b16_d16_hi v2, v5 offset:25600
	v_lshlrev_b32_e32 v5, 5, v24
	v_add3_u32 v11, v11, v12, s62
	v_mul_f32_e32 v12, 0x3fb8aa3b, v13
	v_add3_u32 v5, v14, v15, v5
	ds_write_b16_d16_hi v61, v11 offset:8736
	v_mul_f32_e32 v11, 0xbfb8aa3b, v8
	v_sub_f32_e32 v8, v4, v8
	v_exp_f32_e32 v14, v12
	v_mul_f32_e32 v8, 0x3fb8aa3b, v8
	v_exp_f32_e32 v12, v8
	v_lshlrev_b32_e32 v8, 16, v34
	v_mul_f32_e32 v8, 0x3db504f3, v8
	v_exp_f32_e32 v11, v11
	v_mul_f32_e32 v8, v8, v14
	v_bfe_u32 v14, v8, 16, 1
	v_add3_u32 v8, v8, v14, s62
	v_mul_f32_e32 v14, 0xbfb8aa3b, v13
	v_exp_f32_e32 v16, v14
	v_lshlrev_b32_e32 v14, 16, v33
	v_mul_f32_e32 v11, v11, v14
	v_bfe_u32 v17, v11, 16, 1
	v_sub_f32_e32 v13, v4, v13
	v_lshlrev_b32_e32 v15, 16, v54
	v_add3_u32 v11, v11, v17, s62
	v_mul_f32_e32 v13, 0x3fb8aa3b, v13
	ds_write_b16_d16_hi v61, v11 offset:26144
	ds_write_b16_d16_hi v2, v8 offset:8736
	v_mul_f32_e32 v8, v16, v15
	v_exp_f32_e32 v13, v13
	v_bfe_u32 v11, v8, 16, 1
	v_add3_u32 v8, v8, v11, s62
	ds_write_b16_d16_hi v2, v8 offset:26144
	v_add_f32_e32 v8, v18, v9
	v_mul_f32_e32 v11, 0x3fb8aa3b, v8
	v_pk_mul_f32 v[12:13], v[12:13], v[14:15]
	v_exp_f32_e32 v14, v11
	v_cvt_pk_bf16_f32 v11, v12, v13
	v_lshlrev_b32_e32 v12, 16, v53
	v_mul_f32_e32 v12, 0x3db504f3, v12
	v_mul_f32_e32 v12, v12, v14
	v_bfe_u32 v13, v12, 16, 1
	v_add3_u32 v12, v12, v13, s62
	ds_write_b16_d16_hi v61, v12 offset:9280
	v_mul_f32_e32 v12, 0xbfb8aa3b, v8
	v_add_f32_e32 v13, v19, v9
	v_exp_f32_e32 v16, v12
	v_mul_f32_e32 v12, 0x3fb8aa3b, v13
	v_sub_f32_e32 v8, v4, v8
	v_exp_f32_e32 v14, v12
	v_mul_f32_e32 v8, 0x3fb8aa3b, v8
	v_exp_f32_e32 v12, v8
	v_lshlrev_b32_e32 v8, 16, v51
	v_mul_f32_e32 v8, 0x3db504f3, v8
	v_mul_f32_e32 v8, v8, v14
	v_bfe_u32 v14, v8, 16, 1
	v_add3_u32 v8, v8, v14, s62
	v_mul_f32_e32 v14, 0xbfb8aa3b, v13
	v_exp_f32_e32 v17, v14
	v_lshlrev_b32_e32 v14, 16, v50
	v_mul_f32_e32 v16, v16, v14
	v_sub_f32_e32 v13, v4, v13
	v_bfe_u32 v18, v16, 16, 1
	v_mul_f32_e32 v13, 0x3fb8aa3b, v13
	v_lshlrev_b32_e32 v15, 16, v48
	v_add3_u32 v16, v16, v18, s62
	v_exp_f32_e32 v13, v13
	ds_write_b16_d16_hi v61, v16 offset:26688
	ds_write_b16_d16_hi v2, v8 offset:9280
	v_mul_f32_e32 v8, v17, v15
	v_bfe_u32 v16, v8, 16, 1
	v_add3_u32 v8, v8, v16, s62
	ds_write_b16_d16_hi v2, v8 offset:26688
	v_add_f32_e32 v8, v20, v9
	v_pk_mul_f32 v[12:13], v[12:13], v[14:15]
	v_mul_f32_e32 v14, 0x3fb8aa3b, v8
	v_exp_f32_e32 v14, v14
	v_cvt_pk_bf16_f32 v12, v12, v13
	v_lshlrev_b32_e32 v13, 16, v47
	v_mul_f32_e32 v13, 0x3db504f3, v13
	v_mul_f32_e32 v13, v13, v14
	v_bfe_u32 v14, v13, 16, 1
	v_add_f32_e32 v15, v21, v9
	v_add3_u32 v13, v13, v14, s62
	v_mul_f32_e32 v14, 0x3fb8aa3b, v15
	ds_write_b16_d16_hi v61, v13 offset:9824
	v_mul_f32_e32 v13, 0xbfb8aa3b, v8
	v_sub_f32_e32 v8, v4, v8
	v_exp_f32_e32 v16, v14
	v_mul_f32_e32 v8, 0x3fb8aa3b, v8
	v_exp_f32_e32 v14, v8
	v_lshlrev_b32_e32 v8, 16, v45
	v_mul_f32_e32 v8, 0x3db504f3, v8
	v_exp_f32_e32 v13, v13
	v_mul_f32_e32 v8, v8, v16
	v_bfe_u32 v16, v8, 16, 1
	v_add3_u32 v8, v8, v16, s62
	v_mul_f32_e32 v16, 0xbfb8aa3b, v15
	v_exp_f32_e32 v18, v16
	v_lshlrev_b32_e32 v16, 16, v44
	v_sub_f32_e32 v15, v4, v15
	v_mul_f32_e32 v13, v13, v16
	v_mul_f32_e32 v15, 0x3fb8aa3b, v15
	v_bfe_u32 v19, v13, 16, 1
	v_exp_f32_e32 v15, v15
	v_lshlrev_b32_e32 v17, 16, v46
	v_add3_u32 v13, v13, v19, s62
	ds_write_b16_d16_hi v61, v13 offset:27232
	ds_write_b16_d16_hi v2, v8 offset:9824
	v_mul_f32_e32 v8, v18, v17
	v_bfe_u32 v13, v8, 16, 1
	v_add3_u32 v8, v8, v13, s62
	ds_write_b16_d16_hi v2, v8 offset:27232
	v_pk_mul_f32 v[14:15], v[14:15], v[16:17]
	v_add_f32_e32 v8, v28, v9
; #define LAS __attribute__((address_space(3)))
; __device__ __forceinline__ float bf2f(unsigned short u) { return __uint_as_float((unsigned)u << 16); }
; __device__ __forceinline__ unsigned short f2bf(float f) { unsigned u = __float_as_uint(f); return (unsigned short)((u + 0x7fffu + ((u >> 16) & 1u)) >> 16); }
; __device__ __forceinline__ unsigned pk2(float lo, float hi) { return pg8::cvtpk(lo, hi); }
; __device__ __forceinline__ void gla_intra_unit(const Params& P, LAS unsigned char* lds, int unit) {
;     ...
;       float kd_prev = 0.f;
; #pragma unroll
;       for (int i = 0; i < 16; ++i) { const int c = cgp * 16 + i; const float bc = bcv[i] + off;
;           const float q = bf2f(qraw_[i]), k = bf2f(kraw_[i]);
;           const bf16_t qv = f2bf(q * 0.08838834764831845f * __expf(bc));
;           qd[c * 136 + d] = qv; ki[c * 136 + d] = f2bf(k * __expf(-bc));
;           const float kdv = k * __expf(tot - bc);
;           if (i & 1) *(LAS unsigned*)(kdT + d * 72 + c - 1) = pk2(kd_prev, kdv); else kd_prev = kdv; }
;       if (cgp == 0) decay_g[(size_t)unit * 128 + d] = __expf(tot);
	v_cvt_pk_bf16_f32 v13, v14, v15
	v_mul_f32_e32 v14, 0x3fb8aa3b, v8
	v_exp_f32_e32 v14, v14
	ds_write_b128 v5, v[10:13] offset:43008
	v_lshlrev_b32_e32 v10, 16, v42
	v_mul_f32_e32 v10, 0x3db504f3, v10
	v_mul_f32_e32 v10, v10, v14
	v_bfe_u32 v11, v10, 16, 1
	v_add3_u32 v10, v10, v11, s62
	ds_write_b16_d16_hi v61, v10 offset:10368
	v_mul_f32_e32 v10, 0xbfb8aa3b, v8
	v_add_f32_e32 v11, v49, v9
	v_exp_f32_e32 v14, v10
	v_mul_f32_e32 v10, 0x3fb8aa3b, v11
	v_sub_f32_e32 v8, v4, v8
	v_exp_f32_e32 v12, v10
	v_mul_f32_e32 v8, 0x3fb8aa3b, v8
	v_exp_f32_e32 v10, v8
	v_lshlrev_b32_e32 v8, 16, v39
	v_mul_f32_e32 v8, 0x3db504f3, v8
	v_mul_f32_e32 v8, v8, v12
	v_bfe_u32 v12, v8, 16, 1
	v_add3_u32 v8, v8, v12, s62
	v_mul_f32_e32 v12, 0xbfb8aa3b, v11
	v_exp_f32_e32 v15, v12
	v_lshlrev_b32_e32 v12, 16, v38
	v_mul_f32_e32 v14, v14, v12
	v_sub_f32_e32 v11, v4, v11
	v_bfe_u32 v16, v14, 16, 1
	v_mul_f32_e32 v11, 0x3fb8aa3b, v11
	v_lshlrev_b32_e32 v13, 16, v37
	v_add3_u32 v14, v14, v16, s62
	v_exp_f32_e32 v11, v11
	ds_write_b16_d16_hi v61, v14 offset:27776
	ds_write_b16_d16_hi v2, v8 offset:10368
	v_mul_f32_e32 v8, v15, v13
	v_bfe_u32 v14, v8, 16, 1
	v_add3_u32 v8, v8, v14, s62
	ds_write_b16_d16_hi v2, v8 offset:27776
	v_add_f32_e32 v8, v52, v9
	v_pk_mul_f32 v[10:11], v[10:11], v[12:13]
	v_mul_f32_e32 v12, 0x3fb8aa3b, v8
	v_exp_f32_e32 v12, v12
	v_cvt_pk_bf16_f32 v10, v10, v11
	v_lshlrev_b32_e32 v11, 16, v35
	v_mul_f32_e32 v11, 0x3db504f3, v11
	v_mul_f32_e32 v11, v11, v12
	v_bfe_u32 v12, v11, 16, 1
	v_add_f32_e32 v13, v55, v9
	v_add3_u32 v11, v11, v12, s62
	v_mul_f32_e32 v12, 0x3fb8aa3b, v13
	ds_write_b16_d16_hi v61, v11 offset:10912
	v_mul_f32_e32 v11, 0xbfb8aa3b, v8
	v_sub_f32_e32 v8, v4, v8
	v_exp_f32_e32 v14, v12
	v_mul_f32_e32 v8, 0x3fb8aa3b, v8
	v_exp_f32_e32 v12, v8
	v_lshlrev_b32_e32 v8, 16, v31
	v_mul_f32_e32 v8, 0x3db504f3, v8
	v_exp_f32_e32 v11, v11
	v_mul_f32_e32 v8, v8, v14
	v_bfe_u32 v14, v8, 16, 1
	v_add3_u32 v8, v8, v14, s62
	v_mul_f32_e32 v14, 0xbfb8aa3b, v13
	v_exp_f32_e32 v16, v14
	v_lshlrev_b32_e32 v14, 16, v30
	v_mul_f32_e32 v11, v11, v14
	v_bfe_u32 v17, v11, 16, 1
	v_sub_f32_e32 v13, v4, v13
	v_lshlrev_b32_e32 v15, 16, v32
	v_add3_u32 v11, v11, v17, s62
	v_mul_f32_e32 v13, 0x3fb8aa3b, v13
	ds_write_b16_d16_hi v61, v11 offset:28320
	ds_write_b16_d16_hi v2, v8 offset:10912
	v_mul_f32_e32 v8, v16, v15
	v_exp_f32_e32 v13, v13
	v_bfe_u32 v11, v8, 16, 1
	v_add3_u32 v8, v8, v11, s62
	ds_write_b16_d16_hi v2, v8 offset:28320
	v_add_f32_e32 v8, v57, v9
	v_mul_f32_e32 v11, 0x3fb8aa3b, v8
	v_pk_mul_f32 v[12:13], v[12:13], v[14:15]
	v_exp_f32_e32 v14, v11
	v_cvt_pk_bf16_f32 v11, v12, v13
	v_lshlrev_b32_e32 v12, 16, v29
	v_mul_f32_e32 v12, 0x3db504f3, v12
	v_mul_f32_e32 v12, v12, v14
	v_bfe_u32 v13, v12, 16, 1
	v_add3_u32 v12, v12, v13, s62
	ds_write_b16_d16_hi v61, v12 offset:11456
	v_mul_f32_e32 v12, 0xbfb8aa3b, v8
	v_add_f32_e32 v13, v58, v9
	v_exp_f32_e32 v16, v12
	v_mul_f32_e32 v12, 0x3fb8aa3b, v13
	v_sub_f32_e32 v8, v4, v8
	v_exp_f32_e32 v14, v12
	v_mul_f32_e32 v8, 0x3fb8aa3b, v8
	v_exp_f32_e32 v12, v8
	v_lshlrev_b32_e32 v8, 16, v27
	v_mul_f32_e32 v8, 0x3db504f3, v8
	v_mul_f32_e32 v8, v8, v14
	v_bfe_u32 v14, v8, 16, 1
	v_add3_u32 v8, v8, v14, s62
	v_mul_f32_e32 v14, 0xbfb8aa3b, v13
	v_exp_f32_e32 v17, v14
	v_lshlrev_b32_e32 v14, 16, v26
	v_mul_f32_e32 v16, v16, v14
	v_sub_f32_e32 v13, v4, v13
	v_bfe_u32 v18, v16, 16, 1
	v_mul_f32_e32 v13, 0x3fb8aa3b, v13
	v_lshlrev_b32_e32 v15, 16, v25
	v_add3_u32 v16, v16, v18, s62
	v_exp_f32_e32 v13, v13
	ds_write_b16_d16_hi v61, v16 offset:28864
	ds_write_b16_d16_hi v2, v8 offset:11456
	v_mul_f32_e32 v8, v17, v15
	v_bfe_u32 v16, v8, 16, 1
	v_add3_u32 v8, v8, v16, s62
	ds_write_b16_d16_hi v2, v8 offset:28864
	v_add_f32_e32 v8, v59, v9
	v_pk_mul_f32 v[12:13], v[12:13], v[14:15]
	v_mul_f32_e32 v14, 0x3fb8aa3b, v8
	v_exp_f32_e32 v14, v14
	v_cvt_pk_bf16_f32 v12, v12, v13
	v_lshlrev_b32_e32 v13, 16, v23
	v_mul_f32_e32 v13, 0x3db504f3, v13
	v_mul_f32_e32 v13, v13, v14
	v_bfe_u32 v14, v13, 16, 1
	v_add_f32_e32 v9, v9, v60
	v_add3_u32 v13, v13, v14, s62
	v_mul_f32_e32 v14, 0x3fb8aa3b, v9
	v_exp_f32_e32 v14, v14
	v_lshlrev_b32_e32 v15, 16, v22
	ds_write_b16_d16_hi v61, v13 offset:12000
	v_mul_f32_e32 v13, 0xbfb8aa3b, v8
	v_mul_f32_e32 v15, 0x3db504f3, v15
	v_exp_f32_e32 v13, v13
	v_mul_f32_e32 v14, v15, v14
	v_bfe_u32 v15, v14, 16, 1
	v_sub_f32_e32 v8, v4, v8
	v_add3_u32 v16, v14, v15, s62
	v_mul_f32_e32 v14, 0xbfb8aa3b, v9
	v_sub_f32_e32 v9, v4, v9
	v_mul_f32_e32 v8, 0x3fb8aa3b, v8
	v_exp_f32_e32 v17, v14
	v_mul_f32_e32 v9, 0x3fb8aa3b, v9
	v_lshlrev_b32_e32 v14, 16, v7
	v_exp_f32_e32 v8, v8
	v_exp_f32_e32 v9, v9
	v_lshlrev_b32_e32 v15, 16, v1
	v_mul_f32_e32 v1, v13, v14
	v_bfe_u32 v7, v1, 16, 1
	v_add3_u32 v1, v1, v7, s62
	ds_write_b16_d16_hi v61, v1 offset:29408
	ds_write_b16_d16_hi v2, v16 offset:12000
	v_mul_f32_e32 v1, v17, v15
	v_bfe_u32 v7, v1, 16, 1
	v_pk_mul_f32 v[8:9], v[8:9], v[14:15]
	s_movk_i32 s0, 0x80
	v_add3_u32 v1, v1, v7, s62
	v_cvt_pk_bf16_f32 v13, v8, v9
	v_cmp_gt_u32_e32 vcc, s0, v0
	ds_write_b16_d16_hi v2, v1 offset:29408
	ds_write_b128 v5, v[10:13] offset:43024
	s_and_saveexec_b64 s[0:1], vcc
	s_cbranch_execz .LBB0_426
	v_mul_f32_e32 v1, 0x3fb8aa3b, v4
	v_exp_f32_e32 v2, v1
	v_mov_b32_e32 v1, v105
	v_lshl_add_u64 v[4:5], v[0:1], 2, s[36:37]
	global_store_dword v[4:5], v2, off

; __device__ __forceinline__ unsigned pk2(float lo, float hi) { return pg8::cvtpk(lo, hi); }
; __device__ __forceinline__ float silu_f(float v) { return v * __builtin_amdgcn_rcpf(1.0f + __expf(-v)); }
; __device__ __forceinline__ void gla_inter_unit(const Params& P, LAS unsigned char* lds, int unit) {
;     ...
;     __syncthreads();
;     const float tot = red[cb * 16 + fr] + red[(cb + 4) * 16 + fr];
;     const float rstd = rsqrtf(tot * (1.0f / 256.0f) + RMS_EPS);
; #pragma unroll
;     for (int vbi = 0; vbi < 8; ++vbi) { const int vcol = 16 * (vh * 8 + vbi) + 4 * fq;
;         const f32x4 g = *(const f32x4*)(P.g_gla + vcol); const u32x2 rw = *(const u32x2*)(Z + trow * ZC + ZO_RG + 256 * h + vcol);
;         const float r0 = __uint_as_float(rw.x << 16), r1 = __uint_as_float(rw.x & 0xffff0000u), r2 = __uint_as_float(rw.y << 16), r3 = __uint_as_float(rw.y & 0xffff0000u);
;         u32x2 w; w.x = pk2(o[vbi][0] * rstd * g[0] * silu_f(r0), o[vbi][1] * rstd * g[1] * silu_f(r1)); w.y = pk2(o[vbi][2] * rstd * g[2] * silu_f(r2), o[vbi][3] * rstd * g[3] * silu_f(r3));
;         *(u32x2*)(AO + trow * DM + 1024 + 256 * h + vcol) = w; }
.LBB0_542:
	s_or_b64 exec, exec, s[22:23]
	v_lshlrev_b32_e32 v5, 2, v55
	v_add3_u32 v4, 0, v5, v4
	s_waitcnt lgkmcnt(0)
	s_barrier
	ds_read2st64_b32 v[4:5], v4 offset1:1
	s_mov_b32 s22, 0x800000
	v_lshlrev_b32_e32 v8, 2, v53
	v_or_b32_e32 v10, v8, v40
	v_lshlrev_b64 v[8:9], 13, v[42:43]
	s_waitcnt lgkmcnt(0)
	v_add_f32_e32 v4, v4, v5
	v_fmamk_f32 v4, v4, 0x3b800000, v52
	v_cmp_gt_f32_e32 vcc, s22, v4
	v_mul_f32_e32 v5, 0x4b800000, v4
	v_lshl_add_u64 v[8:9], s[56:57], 0, v[8:9]
	v_cndmask_b32_e32 v4, v4, v5, vcc
	v_rsq_f32_e32 v4, v4
	v_ashrrev_i32_e32 v11, 31, v10
	v_lshl_add_u64 v[12:13], v[8:9], 0, s[68:69]
	v_lshlrev_b64 v[8:9], 12, v[42:43]
	v_lshlrev_b64 v[56:57], 1, v[10:11]
	v_lshl_add_u64 v[8:9], s[58:59], 0, v[8:9]
	v_lshl_add_u64 v[12:13], v[12:13], 0, v[56:57]
	s_mov_b64 s[22:23], 0x1600
	v_mul_f32_e32 v5, 0x45800000, v4
	v_lshl_add_u64 v[54:55], v[8:9], 0, s[68:69]
	v_lshl_add_u64 v[8:9], v[10:11], 2, s[90:91]
	v_lshl_add_u64 v[10:11], v[12:13], 0, s[22:23]
	s_movk_i32 s22, 0x1000
	v_cndmask_b32_e32 v4, v4, v5, vcc
	v_add_co_u32_e32 v12, vcc, s22, v12
	s_nop 0
	v_addc_co_u32_e32 v13, vcc, 0, v13, vcc
	s_mov_b64 s[22:23], 0x6800800
	s_add_i32 s27, s27, s92
	s_add_u32 s52, s52, s54
	s_addc_u32 s53, s53, s55
	s_add_u32 s38, s38, s40
	s_addc_u32 s39, s39, s41
	s_add_i32 s3, s3, s26
	s_cmpk_gt_i32 s27, 0x3ff
	s_waitcnt vmcnt(14)
	v_mov_b32_e32 v40, v176
	v_mov_b32_e32 v41, v177
	v_mov_b32_e32 v42, v178
	v_mov_b32_e32 v43, v179
	v_mov_b32_e32 v12, v210
	v_mov_b32_e32 v13, v211
	v_lshlrev_b32_e32 v14, 16, v12
	v_mul_f32_e32 v5, 0xbfb8aa3b, v14
	v_exp_f32_e32 v5, v5
	v_and_b32_e32 v15, 0xffff0000, v12
	v_lshlrev_b32_e32 v12, 16, v13
	v_and_b32_e32 v13, 0xffff0000, v13
	v_add_f32_e32 v5, 1.0, v5
	v_rcp_f32_e32 v58, v5
	v_pk_mul_f32 v[46:47], v[46:47], v[4:5] op_sel_hi:[1,0]
	v_mul_f32_e32 v5, 0xbfb8aa3b, v15
	v_exp_f32_e32 v5, v5
	v_pk_mul_f32 v[40:41], v[40:41], v[46:47]
	v_add_f32_e32 v5, 1.0, v5
	v_rcp_f32_e32 v59, v5
	v_mul_f32_e32 v5, 0xbfb8aa3b, v12
	v_exp_f32_e32 v5, v5
	v_pk_mul_f32 v[14:15], v[58:59], v[14:15]
	s_nop 0
	v_pk_mul_f32 v[14:15], v[40:41], v[14:15]
	v_add_f32_e32 v5, 1.0, v5
	v_rcp_f32_e32 v40, v5
	v_pk_mul_f32 v[44:45], v[44:45], v[4:5] op_sel_hi:[1,0]
	v_mul_f32_e32 v5, 0xbfb8aa3b, v13
	v_exp_f32_e32 v5, v5
	v_pk_mul_f32 v[42:43], v[42:43], v[44:45]
	v_cvt_pk_bf16_f32 v14, v14, v15
	v_add_f32_e32 v5, 1.0, v5
	v_rcp_f32_e32 v41, v5
	s_nop 0
	v_pk_mul_f32 v[12:13], v[40:41], v[12:13]
	s_nop 0
	v_pk_mul_f32 v[12:13], v[42:43], v[12:13]
	v_lshl_add_u64 v[40:41], v[54:55], 0, v[56:57]
	v_cvt_pk_bf16_f32 v15, v12, v13
	v_lshl_add_u64 v[12:13], v[40:41], 0, s[22:23]
	s_mov_b32 s22, 0x6800000
	v_add_co_u32_e32 v40, vcc, s22, v40
	s_nop 1
	v_addc_co_u32_e32 v41, vcc, 0, v41, vcc
	global_store_dwordx2 v[40:41], v[14:15], off offset:2048
	s_nop 0
	s_waitcnt vmcnt(13)
	v_mov_b32_e32 v40, v180
	v_mov_b32_e32 v41, v181
	v_mov_b32_e32 v42, v182
	v_mov_b32_e32 v43, v183
	v_mov_b32_e32 v14, v212
	v_mov_b32_e32 v15, v213
	v_lshlrev_b32_e32 v44, 16, v14
	v_mul_f32_e32 v5, 0xbfb8aa3b, v44
	v_exp_f32_e32 v5, v5
	v_and_b32_e32 v45, 0xffff0000, v14
	v_add_f32_e32 v5, 1.0, v5
	v_rcp_f32_e32 v46, v5
	v_pk_mul_f32 v[38:39], v[38:39], v[4:5] op_sel_hi:[1,0]
	v_mul_f32_e32 v5, 0xbfb8aa3b, v45
	v_exp_f32_e32 v5, v5
	v_pk_mul_f32 v[38:39], v[40:41], v[38:39]
	v_add_f32_e32 v5, 1.0, v5
	v_rcp_f32_e32 v47, v5
	s_nop 0
	v_pk_mul_f32 v[40:41], v[46:47], v[44:45]
	s_nop 0
	v_pk_mul_f32 v[38:39], v[38:39], v[40:41]
	s_nop 0
	v_cvt_pk_bf16_f32 v14, v38, v39
	v_lshlrev_b32_e32 v38, 16, v15
	v_mul_f32_e32 v5, 0xbfb8aa3b, v38
	v_exp_f32_e32 v5, v5
	v_and_b32_e32 v39, 0xffff0000, v15
	v_add_f32_e32 v5, 1.0, v5
	v_rcp_f32_e32 v40, v5
	v_pk_mul_f32 v[36:37], v[36:37], v[4:5] op_sel_hi:[1,0]
	v_mul_f32_e32 v5, 0xbfb8aa3b, v39
	v_exp_f32_e32 v5, v5
	v_pk_mul_f32 v[36:37], v[42:43], v[36:37]
	v_add_f32_e32 v5, 1.0, v5
	v_rcp_f32_e32 v41, v5
	s_nop 0
	v_pk_mul_f32 v[38:39], v[40:41], v[38:39]
	s_nop 0
	v_pk_mul_f32 v[36:37], v[36:37], v[38:39]
	s_nop 0
	v_cvt_pk_bf16_f32 v15, v36, v37
	global_store_dwordx2 v[12:13], v[14:15], off offset:32
	s_nop 0
	s_waitcnt vmcnt(12)
	v_mov_b32_e32 v36, v184
	v_mov_b32_e32 v37, v185
	v_mov_b32_e32 v38, v186
	v_mov_b32_e32 v39, v187
	v_mov_b32_e32 v14, v214
	v_mov_b32_e32 v15, v215
	v_lshlrev_b32_e32 v40, 16, v14
	v_mul_f32_e32 v5, 0xbfb8aa3b, v40
	v_exp_f32_e32 v5, v5
	v_and_b32_e32 v41, 0xffff0000, v14
	v_add_f32_e32 v5, 1.0, v5
	v_rcp_f32_e32 v42, v5
	v_pk_mul_f32 v[34:35], v[34:35], v[4:5] op_sel_hi:[1,0]
	v_mul_f32_e32 v5, 0xbfb8aa3b, v41
	v_exp_f32_e32 v5, v5
	v_pk_mul_f32 v[34:35], v[36:37], v[34:35]
	v_add_f32_e32 v5, 1.0, v5
	v_rcp_f32_e32 v43, v5
	s_nop 0
	v_pk_mul_f32 v[36:37], v[42:43], v[40:41]
	s_nop 0
	v_pk_mul_f32 v[34:35], v[34:35], v[36:37]
	s_nop 0
	v_cvt_pk_bf16_f32 v14, v34, v35
	v_lshlrev_b32_e32 v34, 16, v15
	v_mul_f32_e32 v5, 0xbfb8aa3b, v34
	v_exp_f32_e32 v5, v5
	v_and_b32_e32 v35, 0xffff0000, v15
	v_add_f32_e32 v5, 1.0, v5
	v_rcp_f32_e32 v36, v5
	v_pk_mul_f32 v[32:33], v[32:33], v[4:5] op_sel_hi:[1,0]
	v_mul_f32_e32 v5, 0xbfb8aa3b, v35
	v_exp_f32_e32 v5, v5
	v_pk_mul_f32 v[32:33], v[38:39], v[32:33]
	v_add_f32_e32 v5, 1.0, v5
	v_rcp_f32_e32 v37, v5
	s_nop 0
	v_pk_mul_f32 v[34:35], v[36:37], v[34:35]
	s_nop 0
	v_pk_mul_f32 v[32:33], v[32:33], v[34:35]
	s_nop 0
	v_cvt_pk_bf16_f32 v15, v32, v33
	global_store_dwordx2 v[12:13], v[14:15], off offset:64
	s_nop 0
	s_waitcnt vmcnt(11)
; __device__ __forceinline__ unsigned pk2(float lo, float hi) { return pg8::cvtpk(lo, hi); }
; __device__ __forceinline__ float silu_f(float v) { return v * __builtin_amdgcn_rcpf(1.0f + __expf(-v)); }
; __device__ __forceinline__ void gla_inter_unit(const Params& P, LAS unsigned char* lds, int unit) {
;     ...
;     for (int vbi = 0; vbi < 8; ++vbi) { const int vcol = 16 * (vh * 8 + vbi) + 4 * fq;
;         const f32x4 g = *(const f32x4*)(P.g_gla + vcol); const u32x2 rw = *(const u32x2*)(Z + trow * ZC + ZO_RG + 256 * h + vcol);
;         const float r0 = __uint_as_float(rw.x << 16), r1 = __uint_as_float(rw.x & 0xffff0000u), r2 = __uint_as_float(rw.y << 16), r3 = __uint_as_float(rw.y & 0xffff0000u);
;         u32x2 w; w.x = pk2(o[vbi][0] * rstd * g[0] * silu_f(r0), o[vbi][1] * rstd * g[1] * silu_f(r1)); w.y = pk2(o[vbi][2] * rstd * g[2] * silu_f(r2), o[vbi][3] * rstd * g[3] * silu_f(r3));
;         *(u32x2*)(AO + trow * DM + 1024 + 256 * h + vcol) = w; }
	v_mov_b32_e32 v32, v188
	v_mov_b32_e32 v33, v189
	v_mov_b32_e32 v34, v190
	v_mov_b32_e32 v35, v191
	v_mov_b32_e32 v14, v216
	v_mov_b32_e32 v15, v217
	v_lshlrev_b32_e32 v36, 16, v14
	v_mul_f32_e32 v5, 0xbfb8aa3b, v36
	v_exp_f32_e32 v5, v5
	v_and_b32_e32 v37, 0xffff0000, v14
	v_add_f32_e32 v5, 1.0, v5
	v_rcp_f32_e32 v38, v5
	v_pk_mul_f32 v[30:31], v[30:31], v[4:5] op_sel_hi:[1,0]
	v_mul_f32_e32 v5, 0xbfb8aa3b, v37
	v_exp_f32_e32 v5, v5
	v_pk_mul_f32 v[30:31], v[30:31], v[32:33]
	v_add_f32_e32 v5, 1.0, v5
	v_rcp_f32_e32 v39, v5
	s_nop 0
	v_pk_mul_f32 v[32:33], v[38:39], v[36:37]
	s_nop 0
	v_pk_mul_f32 v[30:31], v[30:31], v[32:33]
	s_nop 0
	v_cvt_pk_bf16_f32 v14, v30, v31
	v_lshlrev_b32_e32 v30, 16, v15
	v_mul_f32_e32 v5, 0xbfb8aa3b, v30
	v_exp_f32_e32 v5, v5
	v_and_b32_e32 v31, 0xffff0000, v15
	v_add_f32_e32 v5, 1.0, v5
	v_rcp_f32_e32 v32, v5
	v_pk_mul_f32 v[28:29], v[28:29], v[4:5] op_sel_hi:[1,0]
	v_mul_f32_e32 v5, 0xbfb8aa3b, v31
	v_exp_f32_e32 v5, v5
	v_pk_mul_f32 v[28:29], v[28:29], v[34:35]
	v_add_f32_e32 v5, 1.0, v5
	v_rcp_f32_e32 v33, v5
	s_nop 0
	v_pk_mul_f32 v[30:31], v[32:33], v[30:31]
	s_nop 0
	v_pk_mul_f32 v[28:29], v[28:29], v[30:31]
	s_nop 0
	v_cvt_pk_bf16_f32 v15, v28, v29
	global_store_dwordx2 v[12:13], v[14:15], off offset:96
	s_nop 0
	s_waitcnt vmcnt(10)
	v_mov_b32_e32 v28, v192
	v_mov_b32_e32 v29, v193
	v_mov_b32_e32 v30, v194
	v_mov_b32_e32 v31, v195
	v_mov_b32_e32 v14, v218
	v_mov_b32_e32 v15, v219
	v_lshlrev_b32_e32 v32, 16, v14
	v_mul_f32_e32 v5, 0xbfb8aa3b, v32
	v_exp_f32_e32 v5, v5
	v_and_b32_e32 v33, 0xffff0000, v14
	v_add_f32_e32 v5, 1.0, v5
	v_rcp_f32_e32 v34, v5
	v_pk_mul_f32 v[26:27], v[26:27], v[4:5] op_sel_hi:[1,0]
	v_mul_f32_e32 v5, 0xbfb8aa3b, v33
	v_exp_f32_e32 v5, v5
	v_pk_mul_f32 v[26:27], v[26:27], v[28:29]
	v_add_f32_e32 v5, 1.0, v5
	v_rcp_f32_e32 v35, v5
	s_nop 0
	v_pk_mul_f32 v[28:29], v[34:35], v[32:33]
	s_nop 0
	v_pk_mul_f32 v[26:27], v[26:27], v[28:29]
	s_nop 0
	v_cvt_pk_bf16_f32 v14, v26, v27
	v_lshlrev_b32_e32 v26, 16, v15
	v_mul_f32_e32 v5, 0xbfb8aa3b, v26
	v_exp_f32_e32 v5, v5
	v_and_b32_e32 v27, 0xffff0000, v15
	v_add_f32_e32 v5, 1.0, v5
	v_rcp_f32_e32 v28, v5
	v_pk_mul_f32 v[24:25], v[24:25], v[4:5] op_sel_hi:[1,0]
	v_mul_f32_e32 v5, 0xbfb8aa3b, v27
	v_exp_f32_e32 v5, v5
	v_pk_mul_f32 v[24:25], v[24:25], v[30:31]
	v_add_f32_e32 v5, 1.0, v5
	v_rcp_f32_e32 v29, v5
	s_nop 0
	v_pk_mul_f32 v[26:27], v[28:29], v[26:27]
	s_nop 0
	v_pk_mul_f32 v[24:25], v[24:25], v[26:27]
	s_nop 0
	v_cvt_pk_bf16_f32 v15, v24, v25
	global_store_dwordx2 v[12:13], v[14:15], off offset:128
	s_nop 0
	s_waitcnt vmcnt(9)
	v_mov_b32_e32 v24, v196
	v_mov_b32_e32 v25, v197
	v_mov_b32_e32 v26, v198
	v_mov_b32_e32 v27, v199
	v_mov_b32_e32 v14, v220
	v_mov_b32_e32 v15, v221
	v_lshlrev_b32_e32 v28, 16, v14
	v_mul_f32_e32 v5, 0xbfb8aa3b, v28
	v_exp_f32_e32 v5, v5
	v_and_b32_e32 v29, 0xffff0000, v14
	v_add_f32_e32 v5, 1.0, v5
	v_rcp_f32_e32 v30, v5
	v_pk_mul_f32 v[22:23], v[22:23], v[4:5] op_sel_hi:[1,0]
	v_mul_f32_e32 v5, 0xbfb8aa3b, v29
	v_exp_f32_e32 v5, v5
	v_pk_mul_f32 v[22:23], v[22:23], v[24:25]
	v_add_f32_e32 v5, 1.0, v5
	v_rcp_f32_e32 v31, v5
	s_nop 0
	v_pk_mul_f32 v[24:25], v[30:31], v[28:29]
	s_nop 0
	v_pk_mul_f32 v[22:23], v[22:23], v[24:25]
	s_nop 0
	v_cvt_pk_bf16_f32 v14, v22, v23
	v_lshlrev_b32_e32 v22, 16, v15
	v_mul_f32_e32 v5, 0xbfb8aa3b, v22
	v_exp_f32_e32 v5, v5
	v_and_b32_e32 v23, 0xffff0000, v15
	v_add_f32_e32 v5, 1.0, v5
	v_rcp_f32_e32 v24, v5
	v_pk_mul_f32 v[20:21], v[20:21], v[4:5] op_sel_hi:[1,0]
	v_mul_f32_e32 v5, 0xbfb8aa3b, v23
	v_exp_f32_e32 v5, v5
	v_pk_mul_f32 v[20:21], v[20:21], v[26:27]
	v_add_f32_e32 v5, 1.0, v5
	v_rcp_f32_e32 v25, v5
	s_nop 0
	v_pk_mul_f32 v[22:23], v[24:25], v[22:23]
	s_nop 0
	v_pk_mul_f32 v[20:21], v[20:21], v[22:23]
	s_nop 0
	v_cvt_pk_bf16_f32 v15, v20, v21
	global_store_dwordx2 v[12:13], v[14:15], off offset:160
	s_nop 0
	s_waitcnt vmcnt(8)
	v_mov_b32_e32 v20, v200
	v_mov_b32_e32 v21, v201
	v_mov_b32_e32 v22, v202
	v_mov_b32_e32 v23, v203
	v_mov_b32_e32 v14, v222
	v_mov_b32_e32 v15, v223
	v_lshlrev_b32_e32 v24, 16, v14
	v_mul_f32_e32 v5, 0xbfb8aa3b, v24
	v_exp_f32_e32 v5, v5
	v_and_b32_e32 v25, 0xffff0000, v14
	v_add_f32_e32 v5, 1.0, v5
	v_rcp_f32_e32 v26, v5
	v_pk_mul_f32 v[18:19], v[18:19], v[4:5] op_sel_hi:[1,0]
	v_mul_f32_e32 v5, 0xbfb8aa3b, v25
	v_exp_f32_e32 v5, v5
	v_pk_mul_f32 v[18:19], v[18:19], v[20:21]
	v_add_f32_e32 v5, 1.0, v5
	v_rcp_f32_e32 v27, v5
	s_nop 0
	v_pk_mul_f32 v[20:21], v[26:27], v[24:25]
	s_nop 0
	v_pk_mul_f32 v[18:19], v[18:19], v[20:21]
	s_nop 0
	v_cvt_pk_bf16_f32 v14, v18, v19
	v_lshlrev_b32_e32 v18, 16, v15
	v_mul_f32_e32 v5, 0xbfb8aa3b, v18
	v_exp_f32_e32 v5, v5
	v_and_b32_e32 v19, 0xffff0000, v15
	v_add_f32_e32 v5, 1.0, v5
	v_rcp_f32_e32 v20, v5
	v_pk_mul_f32 v[6:7], v[6:7], v[4:5] op_sel_hi:[1,0]
	v_mul_f32_e32 v5, 0xbfb8aa3b, v19
	v_exp_f32_e32 v5, v5
	v_pk_mul_f32 v[6:7], v[6:7], v[22:23]
	v_add_f32_e32 v5, 1.0, v5
	v_rcp_f32_e32 v21, v5
	s_nop 0
	v_pk_mul_f32 v[18:19], v[20:21], v[18:19]
	s_nop 0
	v_pk_mul_f32 v[6:7], v[6:7], v[18:19]
	s_nop 0
	v_cvt_pk_bf16_f32 v15, v6, v7
	global_store_dwordx2 v[12:13], v[14:15], off offset:192
	s_nop 0
	s_waitcnt vmcnt(7)
	v_mov_b32_e32 v6, v204
	v_mov_b32_e32 v7, v205
	v_mov_b32_e32 v8, v206
	v_mov_b32_e32 v9, v207
	v_mov_b32_e32 v10, v224
	v_mov_b32_e32 v11, v225
	v_lshlrev_b32_e32 v14, 16, v10
	v_mul_f32_e32 v5, 0xbfb8aa3b, v14
	v_exp_f32_e32 v5, v5
	v_and_b32_e32 v15, 0xffff0000, v10
	v_add_f32_e32 v5, 1.0, v5
	v_rcp_f32_e32 v18, v5
	v_pk_mul_f32 v[2:3], v[2:3], v[4:5] op_sel_hi:[1,0]
	v_mul_f32_e32 v5, 0xbfb8aa3b, v15
	v_exp_f32_e32 v5, v5
	v_pk_mul_f32 v[2:3], v[2:3], v[6:7]
	v_add_f32_e32 v5, 1.0, v5
	v_rcp_f32_e32 v19, v5
	v_pk_mul_f32 v[0:1], v[0:1], v[4:5] op_sel_hi:[1,0]
	v_pk_mul_f32 v[6:7], v[18:19], v[14:15]
	s_nop 0
	v_pk_mul_f32 v[2:3], v[2:3], v[6:7]
	v_lshlrev_b32_e32 v6, 16, v11
	v_cvt_pk_bf16_f32 v2, v2, v3
	v_mul_f32_e32 v3, 0xbfb8aa3b, v6
	v_exp_f32_e32 v3, v3
	v_and_b32_e32 v7, 0xffff0000, v11
	v_pk_mul_f32 v[0:1], v[0:1], v[8:9]
	v_add_f32_e32 v3, 1.0, v3
	v_rcp_f32_e32 v10, v3
	v_mul_f32_e32 v3, 0xbfb8aa3b, v7
	v_exp_f32_e32 v3, v3
	s_nop 0
	v_add_f32_e32 v3, 1.0, v3
	v_rcp_f32_e32 v11, v3
	s_nop 0
	v_pk_mul_f32 v[4:5], v[10:11], v[6:7]
	s_nop 0
	v_pk_mul_f32 v[0:1], v[0:1], v[4:5]
	s_nop 0
	v_cvt_pk_bf16_f32 v3, v0, v1
	global_store_dwordx2 v[12:13], v[2:3], off offset:224
	s_barrier
	s_cbranch_scc1 .LBB0_545
; #define MFMA16(a, b, c) __builtin_amdgcn_mfma_f32_16x16x32_bf16((a), (b), (c), 0, 0, 0)
; __device__ __forceinline__ void gla_inter_unit(const Params& P, LAS unsigned char* lds, int unit) {
;     ...
;     const int cb = wid & 3, vh = wid >> 2; const size_t trow = t0 + 16 * cb + fr;
;     bf16x8 qf[4];
; #pragma unroll
;     for (int ks = 0; ks < 4; ++ks) qf[ks] = *(const bf16x8*)(qdec_g + ((size_t)unit * 64 + 16 * cb + fr) * 128 + 32 * ks + 8 * fq);
;     f32x4 o[8]; float ss = 0.f;
;     bf16x8 sf[8][4]; u32x2 oiw[8];
; #pragma unroll
;     for (int vbi = 0; vbi < 8; ++vbi) { const int vb = vh * 8 + vbi;
; #pragma unroll
;         for (int ks = 0; ks < 4; ++ks) sf[vbi][ks] = *(const bf16x8*)(ST + ((size_t)unit * 256 + 16 * vb + fr) * 128 + 32 * ks + 8 * fq);
;         oiw[vbi] = *(const u32x2*)(OI + trow * 1024 + 256 * h + 16 * vb + 4 * fq); }
; #pragma unroll
;     for (int vbi = 0; vbi < 8; ++vbi) { f32x4 acc = {0.f, 0.f, 0.f, 0.f};
; #pragma unroll
;         for (int ks = 0; ks < 4; ++ks) acc = MFMA16(sf[vbi][ks], qf[ks], acc);
.LBB0_543:
	v_mov_b32_e32 v54, v168
	v_mov_b32_e32 v3, v17
	v_ashrrev_i32_e32 v4, 1, v54
	v_and_b32_e32 v40, 0xffffff80, v4
	v_and_b32_e32 v152, 15, v54
	v_ashrrev_i32_e32 v41, 31, v40
	v_bfe_u32 v53, v54, 4, 2
	v_or_b32_e32 v6, v40, v152
	v_mov_b32_e32 v7, v41
	v_lshlrev_b32_e32 v2, 4, v53
	v_lshl_add_u64 v[6:7], s[38:39], 0, v[6:7]
	v_lshl_add_u64 v[4:5], s[0:1], 0, v[2:3]
	v_lshlrev_b64 v[6:7], 8, v[6:7]
	v_lshl_add_u64 v[38:39], v[4:5], 0, v[6:7]
	s_movk_i32 s22, 0xa000
	v_lshrrev_b32_e32 v0, 2, v54
	v_add_co_u32_e32 v4, vcc, s22, v38
	v_and_b32_e32 v55, 48, v0
	s_nop 0
	v_addc_co_u32_e32 v5, vcc, -1, v39, vcc
	v_or_b32_e32 v16, v55, v152
	global_load_dwordx4 v[18:21], v[4:5], off offset:-4096
	v_lshl_add_u64 v[0:1], s[52:53], 0, v[16:17]
	v_lshlrev_b64 v[0:1], 8, v[0:1]
	s_movk_i32 s22, 0xc000
	v_lshl_add_u64 v[0:1], s[36:37], 0, v[0:1]
	v_add_co_u32_e32 v80, vcc, s22, v38
	s_movk_i32 s22, 0x9000
	v_lshl_add_u64 v[12:13], v[0:1], 0, v[2:3]
	s_mov_b32 s23, -1
	global_load_dwordx4 v[0:3], v[12:13], off
	global_load_dwordx4 v[22:25], v[4:5], off
	v_lshl_add_u64 v[14:15], v[38:39], 0, s[22:23]
	s_movk_i32 s22, 0xa000
	s_mov_b32 s23, -1
	v_addc_co_u32_e32 v81, vcc, -1, v39, vcc
	v_lshl_add_u64 v[42:43], v[38:39], 0, s[22:23]
	global_load_dwordx4 v[26:29], v[80:81], off offset:-4096
	global_load_dwordx4 v[30:33], v[14:15], off offset:64
	global_load_dwordx4 v[4:7], v[12:13], off offset:64
	global_load_dwordx4 v[34:37], v[42:43], off offset:64
	s_movk_i32 s22, 0xb000
	s_mov_b32 s23, -1
	v_lshl_add_u64 v[76:77], v[38:39], 0, s[22:23]
	global_load_dwordx4 v[44:47], v[76:77], off offset:64
	global_load_dwordx4 v[56:59], v[14:15], off offset:128
	global_load_dwordx4 v[8:11], v[12:13], off offset:128
	global_load_dwordx4 v[60:63], v[42:43], off offset:128
	global_load_dwordx4 v[64:67], v[14:15], off offset:192
	s_nop 0
	global_load_dwordx4 v[12:15], v[12:13], off offset:192
	s_nop 0
	global_load_dwordx4 v[68:71], v[42:43], off offset:192
	global_load_dwordx4 v[72:75], v[76:77], off offset:128
	s_ashr_i32 s22, s27, 9
	global_load_dwordx4 v[80:83], v[80:81], off
	s_ashr_i32 s23, s22, 31
	global_load_dwordx4 v[76:79], v[76:77], off offset:192
	s_and_b32 s33, s52, 0x1fc0
	s_lshl_b64 s[22:23], s[22:23], 13
	s_or_b32 s22, s22, s33
	v_mov_b32_e32 v43, s23
	v_or_b32_e32 v42, s22, v16
	s_and_b32 s43, s3, 0x300
	v_lshlrev_b64 v[86:87], 11, v[42:43]
	s_movk_i32 s22, 0xc000
	s_lshl_b32 s68, s43, 1
	v_lshl_add_u64 v[86:87], s[28:29], 0, v[86:87]
	s_mov_b32 s23, -1
	v_mov_b32_e32 v85, v17
	v_lshlrev_b32_e32 v84, 3, v53
	v_lshl_add_u64 v[86:87], v[86:87], 0, s[68:69]
	v_lshl_add_u64 v[92:93], v[38:39], 0, s[22:23]
	v_lshl_add_u64 v[88:89], v[86:87], 0, v[84:85]
	global_load_dwordx4 v[84:87], v[92:93], off offset:64
	v_lshl_add_u64 v[136:137], v[40:41], 1, v[88:89]
	global_load_dwordx2 v[138:139], v[136:137], off
	global_load_dwordx4 v[88:91], v[92:93], off offset:128
	s_nop 0
	global_load_dwordx4 v[92:95], v[92:93], off offset:192
	s_movk_i32 s22, 0xe000
	v_add_co_u32_e32 v116, vcc, s22, v38
	s_movk_i32 s22, 0xd000
	s_nop 0
	v_addc_co_u32_e32 v117, vcc, -1, v39, vcc
	s_mov_b32 s23, -1
	global_load_dwordx4 v[96:99], v[116:117], off offset:-4096
	global_load_dwordx2 v[140:141], v[136:137], off offset:32
	v_lshl_add_u64 v[112:113], v[38:39], 0, s[22:23]
	global_load_dwordx4 v[100:103], v[112:113], off offset:64
	s_movk_i32 s22, 0xe000
	s_mov_b32 s23, -1
	v_lshl_add_u64 v[124:125], v[38:39], 0, s[22:23]
	global_load_dwordx4 v[104:107], v[112:113], off offset:128
	global_load_dwordx4 v[108:111], v[124:125], off offset:192
	global_load_dwordx2 v[142:143], v[136:137], off offset:64
	v_cmp_lt_i32_e32 vcc, v49, v50
	global_load_dwordx4 v[112:115], v[112:113], off offset:192
	s_waitcnt vmcnt(25)
	v_mfma_f32_16x16x32_bf16 v[22:25], v[22:25], v[0:3], 0
	global_load_dwordx4 v[116:119], v[116:117], off
	s_nop 0
	global_load_dwordx4 v[120:123], v[124:125], off offset:64
	global_load_dwordx2 v[144:145], v[136:137], off offset:96
	v_mfma_f32_16x16x32_bf16 v[18:21], v[18:21], v[0:3], 0
	global_load_dwordx4 v[124:127], v[124:125], off offset:128
	s_nop 0
	global_load_dwordx4 v[128:131], v[38:39], off offset:-4096
	global_load_dwordx2 v[146:147], v[136:137], off offset:128
	global_load_dwordx4 v[132:135], v[38:39], off offset:-4032
	s_waitcnt vmcnt(29)
	v_mfma_f32_16x16x32_bf16 v[18:21], v[30:33], v[4:7], v[18:21]
	s_waitcnt vmcnt(28)
	v_mfma_f32_16x16x32_bf16 v[22:25], v[34:37], v[4:7], v[22:25]
	s_waitcnt vmcnt(16)
; #define MFMA16(a, b, c) __builtin_amdgcn_mfma_f32_16x16x32_bf16((a), (b), (c), 0, 0, 0)
; __device__ __forceinline__ void gla_inter_unit(const Params& P, LAS unsigned char* lds, int unit) {
;     ...
;     for (int vbi = 0; vbi < 8; ++vbi) { const int vb = vh * 8 + vbi;
; #pragma unroll
;         for (int ks = 0; ks < 4; ++ks) sf[vbi][ks] = *(const bf16x8*)(ST + ((size_t)unit * 256 + 16 * vb + fr) * 128 + 32 * ks + 8 * fq);
;         oiw[vbi] = *(const u32x2*)(OI + trow * 1024 + 256 * h + 16 * vb + 4 * fq); }
; #pragma unroll
;     for (int vbi = 0; vbi < 8; ++vbi) { f32x4 acc = {0.f, 0.f, 0.f, 0.f};
; #pragma unroll
;         for (int ks = 0; ks < 4; ++ks) acc = MFMA16(sf[vbi][ks], qf[ks], acc);
;         const u32x2 w = oiw[vbi];
;         acc[0] += __uint_as_float(w.x << 16); acc[1] += __uint_as_float(w.x & 0xffff0000u); acc[2] += __uint_as_float(w.y << 16); acc[3] += __uint_as_float(w.y & 0xffff0000u);
;         o[vbi] = acc; ss += (acc[0] * acc[0] + acc[1] * acc[1]) + (acc[2] * acc[2] + acc[3] * acc[3]); }
;     ...
;     for (int vbi = 0; vbi < 8; ++vbi) { const int vcol = 16 * (vh * 8 + vbi) + 4 * fq;
;         const f32x4 g = *(const f32x4*)(P.g_gla + vcol); const u32x2 rw = *(const u32x2*)(Z + trow * ZC + ZO_RG + 256 * h + vcol);
	v_lshlrev_b32_e32 v34, 16, v138
	v_mfma_f32_16x16x32_bf16 v[18:21], v[56:59], v[8:11], v[18:21]
	global_load_dwordx4 v[56:59], v[38:39], off offset:-3968
	global_load_dwordx2 v[148:149], v[136:137], off offset:160
	v_and_b32_e32 v35, 0xffff0000, v138
	v_mfma_f32_16x16x32_bf16 v[26:29], v[26:29], v[0:3], 0
	v_mfma_f32_16x16x32_bf16 v[22:25], v[60:63], v[8:11], v[22:25]
	global_load_dwordx4 v[60:63], v[38:39], off offset:-3904
	v_mfma_f32_16x16x32_bf16 v[18:21], v[64:67], v[12:15], v[18:21]
	global_load_dwordx4 v[64:67], v[38:39], off
	v_mfma_f32_16x16x32_bf16 v[26:29], v[44:47], v[4:7], v[26:29]
	v_mfma_f32_16x16x32_bf16 v[22:25], v[68:71], v[12:15], v[22:25]
	global_load_dwordx4 v[68:71], v[38:39], off offset:64
	global_load_dwordx2 v[150:151], v[136:137], off offset:192
	s_nop 2
	v_pk_add_f32 v[46:47], v[18:19], v[34:35]
	global_load_dwordx2 v[136:137], v[136:137], off offset:224
	v_mfma_f32_16x16x32_bf16 v[26:29], v[72:75], v[8:11], v[26:29]
	global_load_dwordx4 v[72:75], v[38:39], off offset:128
	v_lshlrev_b32_e32 v18, 16, v139
	v_and_b32_e32 v19, 0xffff0000, v139
	v_mfma_f32_16x16x32_bf16 v[26:29], v[76:79], v[12:15], v[26:29]
	global_load_dwordx4 v[76:79], v[38:39], off offset:192
	v_bfe_u32 v153, v168, 4, 2
	v_ashrrev_i32_e32 v154, 1, v168
	v_and_b32_e32 v154, 0xffffff80, v154
	v_lshl_or_b32 v156, v153, 2, v154
	v_ashrrev_i32_e32 v157, 31, v156
	v_lshrrev_b32_e32 v155, 2, v168
	v_and_b32_e32 v155, 48, v155
	v_and_or_b32 v155, v168, 15, v155
	s_ashr_i32 s100, s27, 9
	s_ashr_i32 s101, s100, 31
	s_lshl_b64 s[100:101], s[100:101], 13
	s_and_b32 s99, s52, 0x1fc0
	s_or_b32 s100, s100, s99
	v_or_b32_e32 v158, s100, v155
	v_mov_b32_e32 v159, s101
	v_lshlrev_b64 v[158:159], 13, v[158:159]
	v_lshl_add_u64 v[158:159], s[56:57], 0, v[158:159]
	s_and_b32 s100, s3, 0x300
	s_lshl_b32 s100, s100, 1
	s_mov_b32 s101, 0
	v_lshl_add_u64 v[158:159], v[158:159], 0, s[100:101]
	v_lshl_add_u64 v[158:159], v[156:157], 1, v[158:159]
	s_mov_b64 s[100:101], 0x1600
	v_lshl_add_u64 v[158:159], v[158:159], 0, s[100:101]
	v_lshl_add_u64 v[160:161], v[156:157], 2, s[90:91]
	global_load_dwordx4 v[176:179], v[160:161], off
	global_load_dwordx2 v[210:211], v[158:159], off
	global_load_dwordx4 v[180:183], v[160:161], off offset:64
	global_load_dwordx2 v[212:213], v[158:159], off offset:32
	global_load_dwordx4 v[184:187], v[160:161], off offset:128
	global_load_dwordx2 v[214:215], v[158:159], off offset:64
	global_load_dwordx4 v[188:191], v[160:161], off offset:192
	global_load_dwordx2 v[216:217], v[158:159], off offset:96
	global_load_dwordx4 v[192:195], v[160:161], off offset:256
	global_load_dwordx2 v[218:219], v[158:159], off offset:128
	global_load_dwordx4 v[196:199], v[160:161], off offset:320
	global_load_dwordx2 v[220:221], v[158:159], off offset:160
	global_load_dwordx4 v[200:203], v[160:161], off offset:384
	global_load_dwordx2 v[222:223], v[158:159], off offset:192
	global_load_dwordx4 v[204:207], v[160:161], off offset:448
	global_load_dwordx2 v[224:225], v[158:159], off offset:224
	v_pk_add_f32 v[44:45], v[20:21], v[18:19]
	v_mfma_f32_16x16x32_bf16 v[30:33], v[80:83], v[0:3], 0
	v_mfma_f32_16x16x32_bf16 v[30:33], v[84:87], v[4:7], v[30:33]
	v_mul_f32_e64 v84, v46, v46
	v_mul_f32_e64 v85, v47, v47
	v_pk_mul_f32 v[86:87], v[44:45], v[44:45]
	s_waitcnt vmcnt(40)
	v_mfma_f32_16x16x32_bf16 v[30:33], v[88:91], v[8:11], v[30:33]
	v_add_f32_e32 v16, v86, v87
	s_waitcnt vmcnt(39)
	v_mfma_f32_16x16x32_bf16 v[18:21], v[92:95], v[12:15], v[30:33]
	s_waitcnt vmcnt(37)
	s_nop 3
	v_lshlrev_b32_e32 v30, 16, v140
	v_and_b32_e32 v31, 0xffff0000, v140
	v_pk_add_f32 v[38:39], v[22:23], v[30:31]
	v_mfma_f32_16x16x32_bf16 v[30:33], v[96:99], v[0:3], 0
	v_lshlrev_b32_e32 v22, 16, v141
	v_and_b32_e32 v23, 0xffff0000, v141
	v_pk_add_f32 v[36:37], v[24:25], v[22:23]
	s_waitcnt vmcnt(36)
	v_mfma_f32_16x16x32_bf16 v[22:25], v[100:103], v[4:7], v[30:33]
	v_mul_f32_e64 v88, v38, v38
	v_mul_f32_e64 v89, v39, v39
	v_pk_mul_f32 v[90:91], v[36:37], v[36:37]
	s_waitcnt vmcnt(33)
	v_lshlrev_b32_e32 v30, 16, v142
	v_and_b32_e32 v31, 0xffff0000, v142
	v_pk_add_f32 v[34:35], v[26:27], v[30:31]
	v_lshlrev_b32_e32 v26, 16, v143
	v_and_b32_e32 v27, 0xffff0000, v143
	v_pk_add_f32 v[32:33], v[28:29], v[26:27]
	s_waitcnt vmcnt(31)
; #define MFMA16(a, b, c) __builtin_amdgcn_mfma_f32_16x16x32_bf16((a), (b), (c), 0, 0, 0)
; __device__ __forceinline__ void gla_inter_unit(const Params& P, LAS unsigned char* lds, int unit) {
;     ...
;     for (int vbi = 0; vbi < 8; ++vbi) { f32x4 acc = {0.f, 0.f, 0.f, 0.f};
; #pragma unroll
;         for (int ks = 0; ks < 4; ++ks) acc = MFMA16(sf[vbi][ks], qf[ks], acc);
;         const u32x2 w = oiw[vbi];
;         acc[0] += __uint_as_float(w.x << 16); acc[1] += __uint_as_float(w.x & 0xffff0000u); acc[2] += __uint_as_float(w.y << 16); acc[3] += __uint_as_float(w.y & 0xffff0000u);
;         o[vbi] = acc; ss += (acc[0] * acc[0] + acc[1] * acc[1]) + (acc[2] * acc[2] + acc[3] * acc[3]); }
;     ss += __shfl_xor(ss, 16); ss += __shfl_xor(ss, 32);
;     if (fq == 0) red[wid * 16 + fr] = ss;
	v_mfma_f32_16x16x32_bf16 v[26:29], v[116:119], v[0:3], 0
	s_waitcnt vmcnt(29)
	v_lshlrev_b32_e32 v30, 16, v144
	v_and_b32_e32 v31, 0xffff0000, v144
	v_pk_add_f32 v[30:31], v[18:19], v[30:31]
	v_mfma_f32_16x16x32_bf16 v[26:29], v[120:123], v[4:7], v[26:29]
	v_lshlrev_b32_e32 v18, 16, v145
	v_and_b32_e32 v19, 0xffff0000, v145
	v_pk_mul_f32 v[92:93], v[34:35], v[34:35]
	s_waitcnt vmcnt(28)
	v_mfma_f32_16x16x32_bf16 v[80:83], v[124:127], v[8:11], v[26:29]
	v_mul_f32_e64 v94, v32, v32
	v_mul_f32_e64 v95, v33, v33
	v_pk_mul_f32 v[96:97], v[30:31], v[30:31]
	v_pk_add_f32 v[28:29], v[20:21], v[18:19]
	v_mfma_f32_16x16x32_bf16 v[18:21], v[108:111], v[12:15], v[80:83]
	s_waitcnt vmcnt(26)
	v_lshlrev_b32_e32 v26, 16, v146
	v_and_b32_e32 v27, 0xffff0000, v146
	v_pk_mul_f32 v[98:99], v[28:29], v[28:29]
	v_mfma_f32_16x16x32_bf16 v[80:83], v[128:131], v[0:3], 0
	s_waitcnt vmcnt(25)
	v_mfma_f32_16x16x32_bf16 v[80:83], v[132:135], v[4:7], v[80:83]
	s_waitcnt vmcnt(21)
	v_mfma_f32_16x16x32_bf16 v[0:3], v[64:67], v[0:3], 0
	v_mfma_f32_16x16x32_bf16 v[56:59], v[56:59], v[8:11], v[80:83]
	s_waitcnt vmcnt(20)
	v_mfma_f32_16x16x32_bf16 v[0:3], v[68:71], v[4:7], v[0:3]
	s_waitcnt vmcnt(19)
	v_lshlrev_b32_e32 v4, 16, v151
	v_and_b32_e32 v5, 0xffff0000, v151
	v_mfma_f32_16x16x32_bf16 v[22:25], v[104:107], v[8:11], v[22:25]
	v_mfma_f32_16x16x32_bf16 v[56:59], v[60:63], v[12:15], v[56:59]
	s_waitcnt vmcnt(17)
	v_mfma_f32_16x16x32_bf16 v[0:3], v[72:75], v[8:11], v[0:3]
	v_mfma_f32_16x16x32_bf16 v[22:25], v[112:115], v[12:15], v[22:25]
	s_nop 4
	v_add_f32_e64 v6, v58, v4
	v_add_f32_e64 v7, v59, v5
	v_pk_mul_f32 v[10:11], v[6:7], v[6:7]
	s_waitcnt vmcnt(16)
	v_mfma_f32_16x16x32_bf16 v[2:5], v[76:79], v[12:15], v[0:3]
	v_add_f32_e32 v14, v88, v89
	v_add_f32_e32 v15, v90, v91
	v_add_f32_e32 v14, v14, v15
	v_add_f32_e32 v15, v84, v85
	v_add_f32_e32 v15, v15, v16
	v_add_f32_e32 v14, v15, v14
	v_add_f32_e32 v15, v92, v93
	v_add_f32_e32 v16, v94, v95
	v_pk_add_f32 v[26:27], v[22:23], v[26:27]
	v_lshlrev_b32_e32 v22, 16, v147
	v_and_b32_e32 v23, 0xffff0000, v147
	v_add_f32_e32 v15, v15, v16
	v_pk_add_f32 v[24:25], v[24:25], v[22:23]
	v_lshlrev_b32_e32 v22, 16, v148
	v_and_b32_e32 v23, 0xffff0000, v148
	v_add_f32_e32 v14, v14, v15
	v_add_f32_e32 v15, v96, v97
	v_add_f32_e32 v16, v98, v99
	v_pk_mul_f32 v[100:101], v[26:27], v[26:27]
	v_pk_mul_f32 v[102:103], v[24:25], v[24:25]
	v_pk_add_f32 v[22:23], v[18:19], v[22:23]
	v_lshlrev_b32_e32 v18, 16, v149
	v_and_b32_e32 v19, 0xffff0000, v149
	v_add_f32_e32 v15, v15, v16
	v_pk_add_f32 v[20:21], v[20:21], v[18:19]
	v_lshlrev_b32_e32 v18, 16, v150
	v_and_b32_e32 v19, 0xffff0000, v150
	v_lshlrev_b32_e32 v0, 16, v136
	v_and_b32_e32 v1, 0xffff0000, v136
	v_add_f32_e32 v14, v14, v15
	v_add_f32_e32 v15, v100, v101
	v_add_f32_e32 v16, v102, v103
	v_pk_mul_f32 v[60:61], v[22:23], v[22:23]
	v_pk_mul_f32 v[62:63], v[20:21], v[20:21]
	v_pk_add_f32 v[18:19], v[56:57], v[18:19]
	v_pk_add_f32 v[2:3], v[2:3], v[0:1]
	v_lshlrev_b32_e32 v0, 16, v137
	v_and_b32_e32 v1, 0xffff0000, v137
	v_add_f32_e32 v15, v15, v16
	v_pk_mul_f32 v[8:9], v[18:19], v[18:19]
	v_pk_add_f32 v[0:1], v[4:5], v[0:1]
	v_add_f32_e32 v14, v14, v15
	v_add_f32_e32 v15, v60, v61
	v_add_f32_e32 v16, v62, v63
	v_pk_mul_f32 v[4:5], v[2:3], v[2:3]
	v_pk_mul_f32 v[12:13], v[0:1], v[0:1]
	v_add_f32_e32 v15, v15, v16
	v_add_f32_e32 v10, v10, v11
	v_add_f32_e32 v8, v8, v9
	v_add_f32_e32 v14, v14, v15
	v_add_f32_e32 v8, v8, v10
	v_add_f32_e32 v9, v12, v13
	v_add_f32_e32 v4, v4, v5
	v_add_f32_e32 v8, v14, v8
	v_add_f32_e32 v4, v4, v9
	v_cndmask_b32_e32 v5, v48, v49, vcc
	v_add_f32_e32 v4, v8, v4
	v_lshlrev_b32_e32 v5, 2, v5
	ds_bpermute_b32 v5, v5, v4
	v_cmp_lt_i32_e32 vcc, v51, v50
	s_waitcnt lgkmcnt(0)
	v_add_f32_e32 v5, v4, v5
	v_cndmask_b32_e32 v4, v48, v51, vcc
	v_lshlrev_b32_e32 v4, 2, v4
	ds_bpermute_b32 v8, v4, v5
	v_cmp_eq_u32_e32 vcc, 0, v53
	v_lshlrev_b32_e32 v4, 2, v152
	s_and_saveexec_b64 s[22:23], vcc
	s_cbranch_execz .LBB0_542
	s_waitcnt lgkmcnt(0)
	v_add_f32_e32 v5, v5, v8
	v_and_b32_e32 v8, 0xffffffc0, v54
	v_add3_u32 v8, 0, v8, v4
	ds_write_b32 v8, v5
	s_branch .LBB0_542
